# in-projection epilogue (both instantiations): the per-row-group s_waitcnt vmcnt(0) in the sigmoid/silu blocks kept only in the first group (it waited for the previous group's store ack 15 times per ga
# speedup vs baseline: 1.0043x; 1.0043x over previous
.LBB0_267:
	v_readlane_b32 s8, v249, 43
	v_readlane_b32 s9, v249, 44
	v_lshl_or_b32 v154, s78, 8, v163
	v_ashrrev_i32_e32 v155, 31, v154
	v_mov_b64_e32 v[156:157], s[8:9]
	v_mad_i64_i32 v[156:157], s[8:9], v152, s76, v[156:157]
	v_cvt_pk_bf16_f32 v174, v153, v168
	v_cndmask_b32_e64 v153, 0, 1, s[38:39]
	v_lshl_add_u64 v[156:157], v[154:155], 1, v[156:157]
	v_cmp_ne_u32_e64 s[8:9], 1, v153
	s_andn2_b64 vcc, exec, s[38:39]
	v_cvt_pk_bf16_f32 v175, v170, v172
	v_cvt_pk_bf16_f32 v176, v167, v169
	v_cvt_pk_bf16_f32 v177, v171, v173
	global_store_dwordx4 v[156:157], v[174:177], off nt
	s_cbranch_vccnz .LBB0_269
	v_mul_f32_e32 v153, 0xbfb8aa3b, v134
	v_mul_f32_e32 v167, 0xbfb8aa3b, v130
	v_exp_f32_e32 v153, v153
	v_exp_f32_e32 v167, v167
	v_add_f32_e32 v153, 1.0, v153
	v_add_f32_e32 v167, 1.0, v167
	v_rcp_f32_e32 v153, v153
	v_rcp_f32_e32 v167, v167
	v_mul_f32_e32 v134, v134, v153
	v_mul_f32_e32 v130, v130, v167
	v_mul_f32_e32 v134, v134, v90
	v_mul_f32_e32 v130, v130, v94
	v_cndmask_b32_e64 v134, v134, v153, s[6:7]
	v_cndmask_b32_e64 v130, v130, v167, s[6:7]
	v_mul_f32_e32 v153, 0xbfb8aa3b, v135
	v_mul_f32_e32 v167, 0xbfb8aa3b, v131
	v_exp_f32_e32 v153, v153
	v_exp_f32_e32 v167, v167
	v_add_f32_e32 v153, 1.0, v153
	v_add_f32_e32 v167, 1.0, v167
	v_rcp_f32_e32 v153, v153
	v_rcp_f32_e32 v167, v167
	v_mul_f32_e32 v135, v135, v153
	v_mul_f32_e32 v131, v131, v167
	v_mul_f32_e32 v135, v135, v91
	v_mul_f32_e32 v131, v131, v95
	v_cndmask_b32_e64 v135, v135, v153, s[6:7]
	v_cndmask_b32_e64 v131, v131, v167, s[6:7]
	v_mul_f32_e32 v153, 0xbfb8aa3b, v136
	v_mul_f32_e32 v167, 0xbfb8aa3b, v132
	v_exp_f32_e32 v153, v153
	v_exp_f32_e32 v167, v167
	v_add_f32_e32 v153, 1.0, v153
	v_add_f32_e32 v167, 1.0, v167
	v_rcp_f32_e32 v153, v153
	v_rcp_f32_e32 v167, v167
	v_mul_f32_e32 v136, v136, v153
	v_mul_f32_e32 v132, v132, v167
	v_mul_f32_e32 v136, v136, v92
	v_mul_f32_e32 v132, v132, v96
	v_cndmask_b32_e64 v136, v136, v153, s[6:7]
	v_cndmask_b32_e64 v132, v132, v167, s[6:7]
	v_mul_f32_e32 v153, 0xbfb8aa3b, v137
	v_mul_f32_e32 v167, 0xbfb8aa3b, v133
	v_exp_f32_e32 v153, v153
	v_exp_f32_e32 v167, v167
	v_add_f32_e32 v153, 1.0, v153
	v_add_f32_e32 v167, 1.0, v167
	v_rcp_f32_e32 v153, v153
	v_rcp_f32_e32 v167, v167
	v_mul_f32_e32 v137, v137, v153
	v_mul_f32_e32 v133, v133, v167
	v_mul_f32_e32 v137, v137, v93
	v_mul_f32_e32 v133, v133, v97
	v_cndmask_b32_e64 v137, v137, v153, s[6:7]
	v_cndmask_b32_e64 v133, v133, v167, s[6:7]
.LBB0_269:
	v_cvt_pk_bf16_f32 v134, v134, v135
	v_cvt_pk_bf16_f32 v135, v136, v137
	v_cvt_pk_bf16_f32 v136, v130, v131
	v_cvt_pk_bf16_f32 v137, v132, v133
	global_store_dwordx4 v[156:157], v[134:137], off offset:256 nt
	s_and_b64 vcc, exec, s[8:9]
	v_mov_b32_e32 v132, v62
	v_mov_b32_e32 v134, v63
	v_mov_b32_e32 v136, v64
	v_mov_b32_e32 v153, v65
	v_mov_b32_e32 v133, v58
	v_mov_b32_e32 v135, v59
	v_mov_b32_e32 v137, v60
	v_mov_b32_e32 v156, v61
	s_cbranch_vccnz .LBB0_271
	v_mul_f32_e32 v130, 0xbfb8aa3b, v62
	v_exp_f32_e32 v130, v130
	v_mul_f32_e32 v131, 0xbfb8aa3b, v58
	v_exp_f32_e32 v131, v131
	v_mul_f32_e32 v133, 0xbfb8aa3b, v63
	v_add_f32_e32 v130, 1.0, v130
	v_rcp_f32_e32 v130, v130
	v_add_f32_e32 v131, 1.0, v131
	v_rcp_f32_e32 v131, v131
	v_mul_f32_e32 v135, 0xbfb8aa3b, v64
	v_mul_f32_e32 v132, v62, v130
	v_mul_f32_e32 v132, v132, v90
	v_mul_f32_e32 v134, v58, v131
	v_cndmask_b32_e64 v132, v132, v130, s[6:7]
	v_exp_f32_e32 v130, v133
	v_mul_f32_e32 v133, v134, v94
	v_mul_f32_e32 v134, 0xbfb8aa3b, v59
	v_exp_f32_e32 v134, v134
	v_add_f32_e32 v130, 1.0, v130
	v_exp_f32_e32 v135, v135
	v_rcp_f32_e32 v130, v130
	v_cndmask_b32_e64 v133, v133, v131, s[6:7]
	v_add_f32_e32 v131, 1.0, v134
	v_rcp_f32_e32 v131, v131
	v_add_f32_e32 v135, 1.0, v135
	v_mul_f32_e32 v134, v63, v130
	v_rcp_f32_e32 v137, v135
	v_mul_f32_e32 v134, v134, v91
	v_mul_f32_e32 v136, 0xbfb8aa3b, v60
	v_cndmask_b32_e64 v134, v134, v130, s[6:7]
	v_mul_f32_e32 v130, v59, v131
	v_exp_f32_e32 v136, v136
	v_mul_f32_e32 v130, v130, v95
	v_cndmask_b32_e64 v135, v130, v131, s[6:7]
	v_mul_f32_e32 v131, v64, v137
	v_mul_f32_e32 v131, v131, v92
	v_add_f32_e32 v130, 1.0, v136
	v_cndmask_b32_e64 v136, v131, v137, s[6:7]
	v_mul_f32_e32 v137, 0xbfb8aa3b, v65
	v_rcp_f32_e32 v130, v130
	v_exp_f32_e32 v137, v137
	v_mul_f32_e32 v153, 0xbfb8aa3b, v61
	v_exp_f32_e32 v153, v153
	v_mul_f32_e32 v131, v60, v130
	v_add_f32_e32 v137, 1.0, v137
	v_mul_f32_e32 v131, v131, v96
	v_rcp_f32_e32 v156, v137
	v_cndmask_b32_e64 v137, v131, v130, s[6:7]
	v_add_f32_e32 v130, 1.0, v153
	v_rcp_f32_e32 v130, v130
	v_mul_f32_e32 v131, v65, v156
	v_mul_f32_e32 v131, v131, v93
	v_cndmask_b32_e64 v153, v131, v156, s[6:7]
	v_mul_f32_e32 v131, v61, v130
	v_mul_f32_e32 v131, v131, v97
	v_cndmask_b32_e64 v156, v131, v130, s[6:7]
.LBB0_271:
	v_readlane_b32 s38, v249, 43
	v_readlane_b32 s39, v249, 44
	v_or_b32_e32 v157, 16, v152
	s_and_b64 vcc, exec, s[8:9]
	v_mov_b64_e32 v[130:131], s[38:39]
	v_mad_i64_i32 v[130:131], s[38:39], v157, s76, v[130:131]
	v_lshl_add_u64 v[130:131], v[154:155], 1, v[130:131]
	v_cvt_pk_bf16_f32 v168, v132, v134
	v_cvt_pk_bf16_f32 v169, v136, v153
	v_cvt_pk_bf16_f32 v170, v133, v135
	v_cvt_pk_bf16_f32 v171, v137, v156
	global_store_dwordx4 v[130:131], v[168:171], off nt
	s_cbranch_vccnz .LBB0_273
	v_mul_f32_e32 v132, 0xbfb8aa3b, v126
	v_mul_f32_e32 v133, 0xbfb8aa3b, v122
	v_exp_f32_e32 v132, v132
	v_exp_f32_e32 v133, v133
	v_add_f32_e32 v132, 1.0, v132
	v_add_f32_e32 v133, 1.0, v133
	v_rcp_f32_e32 v132, v132
	v_rcp_f32_e32 v133, v133
	v_mul_f32_e32 v126, v126, v132
	v_mul_f32_e32 v122, v122, v133
	v_mul_f32_e32 v126, v126, v90
	v_mul_f32_e32 v122, v122, v94
	v_cndmask_b32_e64 v126, v126, v132, s[6:7]
	v_cndmask_b32_e64 v122, v122, v133, s[6:7]
	v_mul_f32_e32 v132, 0xbfb8aa3b, v127
	v_mul_f32_e32 v133, 0xbfb8aa3b, v123
	v_exp_f32_e32 v132, v132
	v_exp_f32_e32 v133, v133
	v_add_f32_e32 v132, 1.0, v132
	v_add_f32_e32 v133, 1.0, v133
	v_rcp_f32_e32 v132, v132
	v_rcp_f32_e32 v133, v133
	v_mul_f32_e32 v127, v127, v132
	v_mul_f32_e32 v123, v123, v133
	v_mul_f32_e32 v127, v127, v91
	v_mul_f32_e32 v123, v123, v95
	v_cndmask_b32_e64 v127, v127, v132, s[6:7]
	v_cndmask_b32_e64 v123, v123, v133, s[6:7]
	v_mul_f32_e32 v132, 0xbfb8aa3b, v128
	v_mul_f32_e32 v133, 0xbfb8aa3b, v124
	v_exp_f32_e32 v132, v132
	v_exp_f32_e32 v133, v133
	v_add_f32_e32 v132, 1.0, v132
	v_add_f32_e32 v133, 1.0, v133
	v_rcp_f32_e32 v132, v132
	v_rcp_f32_e32 v133, v133
	v_mul_f32_e32 v128, v128, v132
	v_mul_f32_e32 v124, v124, v133
	v_mul_f32_e32 v128, v128, v92
	v_mul_f32_e32 v124, v124, v96
	v_cndmask_b32_e64 v128, v128, v132, s[6:7]
	v_cndmask_b32_e64 v124, v124, v133, s[6:7]
	v_mul_f32_e32 v132, 0xbfb8aa3b, v129
	v_mul_f32_e32 v133, 0xbfb8aa3b, v125
	v_exp_f32_e32 v132, v132
	v_exp_f32_e32 v133, v133
	v_add_f32_e32 v132, 1.0, v132
	v_add_f32_e32 v133, 1.0, v133
	v_rcp_f32_e32 v132, v132
	v_rcp_f32_e32 v133, v133
	v_mul_f32_e32 v129, v129, v132
	v_mul_f32_e32 v125, v125, v133
	v_mul_f32_e32 v129, v129, v93
	v_mul_f32_e32 v125, v125, v97
	v_cndmask_b32_e64 v129, v129, v132, s[6:7]
	v_cndmask_b32_e64 v125, v125, v133, s[6:7]
.LBB0_273:
	v_cvt_pk_bf16_f32 v126, v126, v127
	v_cvt_pk_bf16_f32 v127, v128, v129
	v_cvt_pk_bf16_f32 v128, v122, v123
	v_cvt_pk_bf16_f32 v129, v124, v125
	global_store_dwordx4 v[130:131], v[126:129], off offset:256 nt
	s_and_b64 vcc, exec, s[8:9]
	v_mov_b32_e32 v124, v54
	v_mov_b32_e32 v126, v55
	v_mov_b32_e32 v128, v56
	v_mov_b32_e32 v130, v57
	v_mov_b32_e32 v125, v50
	v_mov_b32_e32 v127, v51
	v_mov_b32_e32 v129, v52
	v_mov_b32_e32 v131, v53
	s_cbranch_vccnz .LBB0_275
	v_mul_f32_e32 v122, 0xbfb8aa3b, v54
	v_exp_f32_e32 v122, v122
	v_mul_f32_e32 v123, 0xbfb8aa3b, v50
	v_exp_f32_e32 v123, v123
	v_mul_f32_e32 v125, 0xbfb8aa3b, v55
	v_add_f32_e32 v122, 1.0, v122
	v_rcp_f32_e32 v122, v122
	v_add_f32_e32 v123, 1.0, v123
	v_rcp_f32_e32 v123, v123
	v_mul_f32_e32 v127, 0xbfb8aa3b, v56
	v_mul_f32_e32 v124, v54, v122
	v_mul_f32_e32 v124, v124, v90
	v_mul_f32_e32 v126, v50, v123
	v_cndmask_b32_e64 v124, v124, v122, s[6:7]
	v_exp_f32_e32 v122, v125
	v_mul_f32_e32 v125, v126, v94
	v_mul_f32_e32 v126, 0xbfb8aa3b, v51
	v_exp_f32_e32 v126, v126
	v_add_f32_e32 v122, 1.0, v122
	v_exp_f32_e32 v127, v127
	v_rcp_f32_e32 v122, v122
	v_cndmask_b32_e64 v125, v125, v123, s[6:7]
	v_add_f32_e32 v123, 1.0, v126
	v_rcp_f32_e32 v123, v123
	v_add_f32_e32 v127, 1.0, v127
	v_mul_f32_e32 v126, v55, v122
	v_rcp_f32_e32 v129, v127
	v_mul_f32_e32 v126, v126, v91
	v_mul_f32_e32 v128, 0xbfb8aa3b, v52
	v_cndmask_b32_e64 v126, v126, v122, s[6:7]
	v_mul_f32_e32 v122, v51, v123
	v_exp_f32_e32 v128, v128
	v_mul_f32_e32 v122, v122, v95
	v_cndmask_b32_e64 v127, v122, v123, s[6:7]
	v_mul_f32_e32 v123, v56, v129
	v_mul_f32_e32 v123, v123, v92
	v_add_f32_e32 v122, 1.0, v128
	v_cndmask_b32_e64 v128, v123, v129, s[6:7]
	v_mul_f32_e32 v129, 0xbfb8aa3b, v57
	v_rcp_f32_e32 v122, v122
	v_exp_f32_e32 v129, v129
	v_mul_f32_e32 v130, 0xbfb8aa3b, v53
	v_exp_f32_e32 v130, v130
	v_mul_f32_e32 v123, v52, v122
	v_add_f32_e32 v129, 1.0, v129
	v_mul_f32_e32 v123, v123, v96
	v_rcp_f32_e32 v131, v129
	v_cndmask_b32_e64 v129, v123, v122, s[6:7]
	v_add_f32_e32 v122, 1.0, v130
	v_rcp_f32_e32 v122, v122
	v_mul_f32_e32 v123, v57, v131
	v_mul_f32_e32 v123, v123, v93
	v_cndmask_b32_e64 v130, v123, v131, s[6:7]
	v_mul_f32_e32 v123, v53, v122
	v_mul_f32_e32 v123, v123, v97
	v_cndmask_b32_e64 v131, v123, v122, s[6:7]
.LBB0_275:
	v_readlane_b32 s38, v249, 43
	v_readlane_b32 s39, v249, 44
	v_or_b32_e32 v132, 32, v152
	s_and_b64 vcc, exec, s[8:9]
	v_mov_b64_e32 v[122:123], s[38:39]
	v_mad_i64_i32 v[122:123], s[38:39], v132, s76, v[122:123]
	v_lshl_add_u64 v[122:123], v[154:155], 1, v[122:123]
	v_cvt_pk_bf16_f32 v132, v124, v126
	v_cvt_pk_bf16_f32 v133, v128, v130
	v_cvt_pk_bf16_f32 v134, v125, v127
	v_cvt_pk_bf16_f32 v135, v129, v131
	global_store_dwordx4 v[122:123], v[132:135], off nt
	s_cbranch_vccnz .LBB0_277
	v_mul_f32_e32 v124, 0xbfb8aa3b, v118
	v_mul_f32_e32 v125, 0xbfb8aa3b, v114
	v_exp_f32_e32 v124, v124
	v_exp_f32_e32 v125, v125
	v_add_f32_e32 v124, 1.0, v124
	v_add_f32_e32 v125, 1.0, v125
	v_rcp_f32_e32 v124, v124
	v_rcp_f32_e32 v125, v125
	v_mul_f32_e32 v118, v118, v124
	v_mul_f32_e32 v114, v114, v125
	v_mul_f32_e32 v118, v118, v90
	v_mul_f32_e32 v114, v114, v94
	v_cndmask_b32_e64 v118, v118, v124, s[6:7]
	v_cndmask_b32_e64 v114, v114, v125, s[6:7]
	v_mul_f32_e32 v124, 0xbfb8aa3b, v119
	v_mul_f32_e32 v125, 0xbfb8aa3b, v115
	v_exp_f32_e32 v124, v124
	v_exp_f32_e32 v125, v125
	v_add_f32_e32 v124, 1.0, v124
	v_add_f32_e32 v125, 1.0, v125
	v_rcp_f32_e32 v124, v124
	v_rcp_f32_e32 v125, v125
	v_mul_f32_e32 v119, v119, v124
	v_mul_f32_e32 v115, v115, v125
	v_mul_f32_e32 v119, v119, v91
	v_mul_f32_e32 v115, v115, v95
	v_cndmask_b32_e64 v119, v119, v124, s[6:7]
	v_cndmask_b32_e64 v115, v115, v125, s[6:7]
	v_mul_f32_e32 v124, 0xbfb8aa3b, v120
	v_mul_f32_e32 v125, 0xbfb8aa3b, v116
	v_exp_f32_e32 v124, v124
	v_exp_f32_e32 v125, v125
	v_add_f32_e32 v124, 1.0, v124
	v_add_f32_e32 v125, 1.0, v125
	v_rcp_f32_e32 v124, v124
	v_rcp_f32_e32 v125, v125
	v_mul_f32_e32 v120, v120, v124
	v_mul_f32_e32 v116, v116, v125
	v_mul_f32_e32 v120, v120, v92
	v_mul_f32_e32 v116, v116, v96
	v_cndmask_b32_e64 v120, v120, v124, s[6:7]
	v_cndmask_b32_e64 v116, v116, v125, s[6:7]
	v_mul_f32_e32 v124, 0xbfb8aa3b, v121
	v_mul_f32_e32 v125, 0xbfb8aa3b, v117
	v_exp_f32_e32 v124, v124
	v_exp_f32_e32 v125, v125
	v_add_f32_e32 v124, 1.0, v124
	v_add_f32_e32 v125, 1.0, v125
	v_rcp_f32_e32 v124, v124
	v_rcp_f32_e32 v125, v125
	v_mul_f32_e32 v121, v121, v124
	v_mul_f32_e32 v117, v117, v125
	v_mul_f32_e32 v121, v121, v93
	v_mul_f32_e32 v117, v117, v97
	v_cndmask_b32_e64 v121, v121, v124, s[6:7]
	v_cndmask_b32_e64 v117, v117, v125, s[6:7]
.LBB0_277:
	v_cvt_pk_bf16_f32 v118, v118, v119
	v_cvt_pk_bf16_f32 v119, v120, v121
	v_cvt_pk_bf16_f32 v120, v114, v115
	v_cvt_pk_bf16_f32 v121, v116, v117
	global_store_dwordx4 v[122:123], v[118:121], off offset:256 nt
	s_and_b64 vcc, exec, s[8:9]
	v_mov_b32_e32 v116, v46
	v_mov_b32_e32 v118, v47
	v_mov_b32_e32 v120, v48
	v_mov_b32_e32 v122, v49
	v_mov_b32_e32 v117, v42
	v_mov_b32_e32 v119, v43
	v_mov_b32_e32 v121, v44
	v_mov_b32_e32 v123, v45
	s_cbranch_vccnz .LBB0_279
	v_mul_f32_e32 v114, 0xbfb8aa3b, v46
	v_exp_f32_e32 v114, v114
	v_mul_f32_e32 v115, 0xbfb8aa3b, v42
	v_exp_f32_e32 v115, v115
	v_mul_f32_e32 v117, 0xbfb8aa3b, v47
	v_add_f32_e32 v114, 1.0, v114
	v_rcp_f32_e32 v114, v114
	v_add_f32_e32 v115, 1.0, v115
	v_rcp_f32_e32 v115, v115
	v_mul_f32_e32 v119, 0xbfb8aa3b, v48
	v_mul_f32_e32 v116, v46, v114
	v_mul_f32_e32 v116, v116, v90
	v_mul_f32_e32 v118, v42, v115
	v_cndmask_b32_e64 v116, v116, v114, s[6:7]
	v_exp_f32_e32 v114, v117
	v_mul_f32_e32 v117, v118, v94
	v_mul_f32_e32 v118, 0xbfb8aa3b, v43
	v_exp_f32_e32 v118, v118
	v_add_f32_e32 v114, 1.0, v114
	v_exp_f32_e32 v119, v119
	v_rcp_f32_e32 v114, v114
	v_cndmask_b32_e64 v117, v117, v115, s[6:7]
	v_add_f32_e32 v115, 1.0, v118
	v_rcp_f32_e32 v115, v115
	v_add_f32_e32 v119, 1.0, v119
	v_mul_f32_e32 v118, v47, v114
	v_rcp_f32_e32 v121, v119
	v_mul_f32_e32 v118, v118, v91
	v_mul_f32_e32 v120, 0xbfb8aa3b, v44
	v_cndmask_b32_e64 v118, v118, v114, s[6:7]
	v_mul_f32_e32 v114, v43, v115
	v_exp_f32_e32 v120, v120
	v_mul_f32_e32 v114, v114, v95
	v_cndmask_b32_e64 v119, v114, v115, s[6:7]
	v_mul_f32_e32 v115, v48, v121
	v_mul_f32_e32 v115, v115, v92
	v_add_f32_e32 v114, 1.0, v120
	v_cndmask_b32_e64 v120, v115, v121, s[6:7]
	v_mul_f32_e32 v121, 0xbfb8aa3b, v49
	v_rcp_f32_e32 v114, v114
	v_exp_f32_e32 v121, v121
	v_mul_f32_e32 v122, 0xbfb8aa3b, v45
	v_exp_f32_e32 v122, v122
	v_mul_f32_e32 v115, v44, v114
	v_add_f32_e32 v121, 1.0, v121
	v_mul_f32_e32 v115, v115, v96
	v_rcp_f32_e32 v123, v121
	v_cndmask_b32_e64 v121, v115, v114, s[6:7]
	v_add_f32_e32 v114, 1.0, v122
	v_rcp_f32_e32 v114, v114
	v_mul_f32_e32 v115, v49, v123
	v_mul_f32_e32 v115, v115, v93
	v_cndmask_b32_e64 v122, v115, v123, s[6:7]
	v_mul_f32_e32 v115, v45, v114
	v_mul_f32_e32 v115, v115, v97
	v_cndmask_b32_e64 v123, v115, v114, s[6:7]
.LBB0_279:
	v_readlane_b32 s38, v249, 43
	v_readlane_b32 s39, v249, 44
	v_or_b32_e32 v124, 48, v152
	s_and_b64 vcc, exec, s[8:9]
	v_mov_b64_e32 v[114:115], s[38:39]
	v_mad_i64_i32 v[114:115], s[38:39], v124, s76, v[114:115]
	v_lshl_add_u64 v[114:115], v[154:155], 1, v[114:115]
	v_cvt_pk_bf16_f32 v124, v116, v118
	v_cvt_pk_bf16_f32 v125, v120, v122
	v_cvt_pk_bf16_f32 v126, v117, v119
	v_cvt_pk_bf16_f32 v127, v121, v123
	global_store_dwordx4 v[114:115], v[124:127], off nt
	s_cbranch_vccnz .LBB0_281
	v_mul_f32_e32 v116, 0xbfb8aa3b, v110
	v_mul_f32_e32 v117, 0xbfb8aa3b, v106
	v_exp_f32_e32 v116, v116
	v_exp_f32_e32 v117, v117
	v_add_f32_e32 v116, 1.0, v116
	v_add_f32_e32 v117, 1.0, v117
	v_rcp_f32_e32 v116, v116
	v_rcp_f32_e32 v117, v117
	v_mul_f32_e32 v110, v110, v116
	v_mul_f32_e32 v106, v106, v117
	v_mul_f32_e32 v110, v110, v90
	v_mul_f32_e32 v106, v106, v94
	v_cndmask_b32_e64 v110, v110, v116, s[6:7]
	v_cndmask_b32_e64 v106, v106, v117, s[6:7]
	v_mul_f32_e32 v116, 0xbfb8aa3b, v111
	v_mul_f32_e32 v117, 0xbfb8aa3b, v107
	v_exp_f32_e32 v116, v116
	v_exp_f32_e32 v117, v117
	v_add_f32_e32 v116, 1.0, v116
	v_add_f32_e32 v117, 1.0, v117
	v_rcp_f32_e32 v116, v116
	v_rcp_f32_e32 v117, v117
	v_mul_f32_e32 v111, v111, v116
	v_mul_f32_e32 v107, v107, v117
	v_mul_f32_e32 v111, v111, v91
	v_mul_f32_e32 v107, v107, v95
	v_cndmask_b32_e64 v111, v111, v116, s[6:7]
	v_cndmask_b32_e64 v107, v107, v117, s[6:7]
	v_mul_f32_e32 v116, 0xbfb8aa3b, v112
	v_mul_f32_e32 v117, 0xbfb8aa3b, v108
	v_exp_f32_e32 v116, v116
	v_exp_f32_e32 v117, v117
	v_add_f32_e32 v116, 1.0, v116
	v_add_f32_e32 v117, 1.0, v117
	v_rcp_f32_e32 v116, v116
	v_rcp_f32_e32 v117, v117
	v_mul_f32_e32 v112, v112, v116
	v_mul_f32_e32 v108, v108, v117
	v_mul_f32_e32 v112, v112, v92
	v_mul_f32_e32 v108, v108, v96
	v_cndmask_b32_e64 v112, v112, v116, s[6:7]
	v_cndmask_b32_e64 v108, v108, v117, s[6:7]
	v_mul_f32_e32 v116, 0xbfb8aa3b, v113
	v_mul_f32_e32 v117, 0xbfb8aa3b, v109
	v_exp_f32_e32 v116, v116
	v_exp_f32_e32 v117, v117
	v_add_f32_e32 v116, 1.0, v116
	v_add_f32_e32 v117, 1.0, v117
	v_rcp_f32_e32 v116, v116
	v_rcp_f32_e32 v117, v117
	v_mul_f32_e32 v113, v113, v116
	v_mul_f32_e32 v109, v109, v117
	v_mul_f32_e32 v113, v113, v93
	v_mul_f32_e32 v109, v109, v97
	v_cndmask_b32_e64 v113, v113, v116, s[6:7]
	v_cndmask_b32_e64 v109, v109, v117, s[6:7]
.LBB0_281:
	v_cvt_pk_bf16_f32 v110, v110, v111
	v_cvt_pk_bf16_f32 v111, v112, v113
	v_cvt_pk_bf16_f32 v112, v106, v107
	v_cvt_pk_bf16_f32 v113, v108, v109
	global_store_dwordx4 v[114:115], v[110:113], off offset:256 nt
	s_and_b64 vcc, exec, s[8:9]
	v_mov_b32_e32 v108, v34
	v_mov_b32_e32 v110, v35
	v_mov_b32_e32 v112, v36
	v_mov_b32_e32 v114, v37
	v_mov_b32_e32 v109, v26
	v_mov_b32_e32 v111, v27
	v_mov_b32_e32 v113, v28
	v_mov_b32_e32 v115, v29
	s_cbranch_vccnz .LBB0_283
	v_mul_f32_e32 v106, 0xbfb8aa3b, v34
	v_exp_f32_e32 v106, v106
	v_mul_f32_e32 v107, 0xbfb8aa3b, v26
	v_exp_f32_e32 v107, v107
	v_mul_f32_e32 v109, 0xbfb8aa3b, v35
	v_add_f32_e32 v106, 1.0, v106
	v_rcp_f32_e32 v106, v106
	v_add_f32_e32 v107, 1.0, v107
	v_rcp_f32_e32 v107, v107
	v_mul_f32_e32 v111, 0xbfb8aa3b, v36
	v_mul_f32_e32 v108, v34, v106
	v_mul_f32_e32 v108, v108, v90
	v_mul_f32_e32 v110, v26, v107
	v_cndmask_b32_e64 v108, v108, v106, s[6:7]
	v_exp_f32_e32 v106, v109
	v_mul_f32_e32 v109, v110, v94
	v_mul_f32_e32 v110, 0xbfb8aa3b, v27
	v_exp_f32_e32 v110, v110
	v_add_f32_e32 v106, 1.0, v106
	v_exp_f32_e32 v111, v111
	v_rcp_f32_e32 v106, v106
	v_cndmask_b32_e64 v109, v109, v107, s[6:7]
	v_add_f32_e32 v107, 1.0, v110
	v_rcp_f32_e32 v107, v107
	v_add_f32_e32 v111, 1.0, v111
	v_mul_f32_e32 v110, v35, v106
	v_rcp_f32_e32 v113, v111
	v_mul_f32_e32 v110, v110, v91
	v_mul_f32_e32 v112, 0xbfb8aa3b, v28
	v_cndmask_b32_e64 v110, v110, v106, s[6:7]
	v_mul_f32_e32 v106, v27, v107
	v_exp_f32_e32 v112, v112
	v_mul_f32_e32 v106, v106, v95
	v_cndmask_b32_e64 v111, v106, v107, s[6:7]
	v_mul_f32_e32 v107, v36, v113
	v_mul_f32_e32 v107, v107, v92
	v_add_f32_e32 v106, 1.0, v112
	v_cndmask_b32_e64 v112, v107, v113, s[6:7]
	v_mul_f32_e32 v113, 0xbfb8aa3b, v37
	v_rcp_f32_e32 v106, v106
	v_exp_f32_e32 v113, v113
	v_mul_f32_e32 v114, 0xbfb8aa3b, v29
	v_exp_f32_e32 v114, v114
	v_mul_f32_e32 v107, v28, v106
	v_add_f32_e32 v113, 1.0, v113
	v_mul_f32_e32 v107, v107, v96
	v_rcp_f32_e32 v115, v113
	v_cndmask_b32_e64 v113, v107, v106, s[6:7]
	v_add_f32_e32 v106, 1.0, v114
	v_rcp_f32_e32 v106, v106
	v_mul_f32_e32 v107, v37, v115
	v_mul_f32_e32 v107, v107, v93
	v_cndmask_b32_e64 v114, v107, v115, s[6:7]
	v_mul_f32_e32 v107, v29, v106
	v_mul_f32_e32 v107, v107, v97
	v_cndmask_b32_e64 v115, v107, v106, s[6:7]
.LBB0_283:
	v_readlane_b32 s38, v249, 43
	v_readlane_b32 s39, v249, 44
	v_add_u32_e32 v116, 0x80, v152
	s_and_b64 vcc, exec, s[8:9]
	v_mov_b64_e32 v[106:107], s[38:39]
	v_mad_i64_i32 v[106:107], s[38:39], v116, s76, v[106:107]
	v_lshl_add_u64 v[106:107], v[154:155], 1, v[106:107]
	v_cvt_pk_bf16_f32 v116, v108, v110
	v_cvt_pk_bf16_f32 v117, v112, v114
	v_cvt_pk_bf16_f32 v118, v109, v111
	v_cvt_pk_bf16_f32 v119, v113, v115
	global_store_dwordx4 v[106:107], v[116:119], off nt
	s_cbranch_vccnz .LBB0_285
	v_mul_f32_e32 v108, 0xbfb8aa3b, v102
	v_mul_f32_e32 v109, 0xbfb8aa3b, v98
	v_exp_f32_e32 v108, v108
	v_exp_f32_e32 v109, v109
	v_add_f32_e32 v108, 1.0, v108
	v_add_f32_e32 v109, 1.0, v109
	v_rcp_f32_e32 v108, v108
	v_rcp_f32_e32 v109, v109
	v_mul_f32_e32 v102, v102, v108
	v_mul_f32_e32 v98, v98, v109
	v_mul_f32_e32 v102, v102, v90
	v_mul_f32_e32 v98, v98, v94
	v_cndmask_b32_e64 v102, v102, v108, s[6:7]
	v_cndmask_b32_e64 v98, v98, v109, s[6:7]
	v_mul_f32_e32 v108, 0xbfb8aa3b, v103
	v_mul_f32_e32 v109, 0xbfb8aa3b, v99
	v_exp_f32_e32 v108, v108
	v_exp_f32_e32 v109, v109
	v_add_f32_e32 v108, 1.0, v108
	v_add_f32_e32 v109, 1.0, v109
	v_rcp_f32_e32 v108, v108
	v_rcp_f32_e32 v109, v109
	v_mul_f32_e32 v103, v103, v108
	v_mul_f32_e32 v99, v99, v109
	v_mul_f32_e32 v103, v103, v91
	v_mul_f32_e32 v99, v99, v95
	v_cndmask_b32_e64 v103, v103, v108, s[6:7]
	v_cndmask_b32_e64 v99, v99, v109, s[6:7]
	v_mul_f32_e32 v108, 0xbfb8aa3b, v104
	v_mul_f32_e32 v109, 0xbfb8aa3b, v100
	v_exp_f32_e32 v108, v108
	v_exp_f32_e32 v109, v109
	v_add_f32_e32 v108, 1.0, v108
	v_add_f32_e32 v109, 1.0, v109
	v_rcp_f32_e32 v108, v108
	v_rcp_f32_e32 v109, v109
	v_mul_f32_e32 v104, v104, v108
	v_mul_f32_e32 v100, v100, v109
	v_mul_f32_e32 v104, v104, v92
	v_mul_f32_e32 v100, v100, v96
	v_cndmask_b32_e64 v104, v104, v108, s[6:7]
	v_cndmask_b32_e64 v100, v100, v109, s[6:7]
	v_mul_f32_e32 v108, 0xbfb8aa3b, v105
	v_mul_f32_e32 v109, 0xbfb8aa3b, v101
	v_exp_f32_e32 v108, v108
	v_exp_f32_e32 v109, v109
	v_add_f32_e32 v108, 1.0, v108
	v_add_f32_e32 v109, 1.0, v109
	v_rcp_f32_e32 v108, v108
	v_rcp_f32_e32 v109, v109
	v_mul_f32_e32 v105, v105, v108
	v_mul_f32_e32 v101, v101, v109
	v_mul_f32_e32 v105, v105, v93
	v_mul_f32_e32 v101, v101, v97
	v_cndmask_b32_e64 v105, v105, v108, s[6:7]
	v_cndmask_b32_e64 v101, v101, v109, s[6:7]
.LBB0_285:
	v_cvt_pk_bf16_f32 v102, v102, v103
	v_cvt_pk_bf16_f32 v103, v104, v105
	v_cvt_pk_bf16_f32 v104, v98, v99
	v_cvt_pk_bf16_f32 v105, v100, v101
	global_store_dwordx4 v[106:107], v[102:105], off offset:256 nt
	s_and_b64 vcc, exec, s[8:9]
	v_mov_b32_e32 v100, v22
	v_mov_b32_e32 v102, v23
	v_mov_b32_e32 v104, v24
	v_mov_b32_e32 v106, v25
	v_mov_b32_e32 v101, v18
	v_mov_b32_e32 v103, v19
	v_mov_b32_e32 v105, v20
	v_mov_b32_e32 v107, v21
	s_cbranch_vccnz .LBB0_287
	v_mul_f32_e32 v98, 0xbfb8aa3b, v22
	v_exp_f32_e32 v98, v98
	v_mul_f32_e32 v99, 0xbfb8aa3b, v18
	v_exp_f32_e32 v99, v99
	v_mul_f32_e32 v101, 0xbfb8aa3b, v23
	v_add_f32_e32 v98, 1.0, v98
	v_rcp_f32_e32 v98, v98
	v_add_f32_e32 v99, 1.0, v99
	v_rcp_f32_e32 v99, v99
	v_mul_f32_e32 v103, 0xbfb8aa3b, v24
	v_mul_f32_e32 v100, v22, v98
	v_mul_f32_e32 v100, v100, v90
	v_mul_f32_e32 v102, v18, v99
	v_cndmask_b32_e64 v100, v100, v98, s[6:7]
	v_exp_f32_e32 v98, v101
	v_mul_f32_e32 v101, v102, v94
	v_mul_f32_e32 v102, 0xbfb8aa3b, v19
	v_exp_f32_e32 v102, v102
	v_add_f32_e32 v98, 1.0, v98
	v_exp_f32_e32 v103, v103
	v_rcp_f32_e32 v98, v98
	v_cndmask_b32_e64 v101, v101, v99, s[6:7]
	v_add_f32_e32 v99, 1.0, v102
	v_rcp_f32_e32 v99, v99
	v_add_f32_e32 v103, 1.0, v103
	v_mul_f32_e32 v102, v23, v98
	v_rcp_f32_e32 v105, v103
	v_mul_f32_e32 v102, v102, v91
	v_mul_f32_e32 v104, 0xbfb8aa3b, v20
	v_cndmask_b32_e64 v102, v102, v98, s[6:7]
	v_mul_f32_e32 v98, v19, v99
	v_exp_f32_e32 v104, v104
	v_mul_f32_e32 v98, v98, v95
	v_cndmask_b32_e64 v103, v98, v99, s[6:7]
	v_mul_f32_e32 v99, v24, v105
	v_mul_f32_e32 v99, v99, v92
	v_add_f32_e32 v98, 1.0, v104
	v_cndmask_b32_e64 v104, v99, v105, s[6:7]
	v_mul_f32_e32 v105, 0xbfb8aa3b, v25
	v_rcp_f32_e32 v98, v98
	v_exp_f32_e32 v105, v105
	v_mul_f32_e32 v106, 0xbfb8aa3b, v21
	v_exp_f32_e32 v106, v106
	v_mul_f32_e32 v99, v20, v98
	v_add_f32_e32 v105, 1.0, v105
	v_mul_f32_e32 v99, v99, v96
	v_rcp_f32_e32 v107, v105
	v_cndmask_b32_e64 v105, v99, v98, s[6:7]
	v_add_f32_e32 v98, 1.0, v106
	v_rcp_f32_e32 v98, v98
	v_mul_f32_e32 v99, v25, v107
	v_mul_f32_e32 v99, v99, v93
	v_cndmask_b32_e64 v106, v99, v107, s[6:7]
	v_mul_f32_e32 v99, v21, v98
	v_mul_f32_e32 v99, v99, v97
	v_cndmask_b32_e64 v107, v99, v98, s[6:7]
.LBB0_287:
	v_readlane_b32 s38, v249, 43
	v_readlane_b32 s39, v249, 44
	v_add_u32_e32 v108, 0x90, v152
	s_and_b64 vcc, exec, s[8:9]
	v_mov_b64_e32 v[98:99], s[38:39]
	v_mad_i64_i32 v[98:99], s[38:39], v108, s76, v[98:99]
	v_lshl_add_u64 v[98:99], v[154:155], 1, v[98:99]
	v_cvt_pk_bf16_f32 v108, v100, v102
	v_cvt_pk_bf16_f32 v109, v104, v106
	v_cvt_pk_bf16_f32 v110, v101, v103
	v_cvt_pk_bf16_f32 v111, v105, v107
	global_store_dwordx4 v[98:99], v[108:111], off nt
	s_cbranch_vccnz .LBB0_289
	v_mul_f32_e32 v100, 0xbfb8aa3b, v86
	v_mul_f32_e32 v101, 0xbfb8aa3b, v82
	v_exp_f32_e32 v100, v100
	v_exp_f32_e32 v101, v101
	v_add_f32_e32 v100, 1.0, v100
	v_add_f32_e32 v101, 1.0, v101
	v_rcp_f32_e32 v100, v100
	v_rcp_f32_e32 v101, v101
	v_mul_f32_e32 v86, v86, v100
	v_mul_f32_e32 v82, v82, v101
	v_mul_f32_e32 v86, v86, v90
	v_mul_f32_e32 v82, v82, v94
	v_cndmask_b32_e64 v86, v86, v100, s[6:7]
	v_cndmask_b32_e64 v82, v82, v101, s[6:7]
	v_mul_f32_e32 v100, 0xbfb8aa3b, v87
	v_mul_f32_e32 v101, 0xbfb8aa3b, v83
	v_exp_f32_e32 v100, v100
	v_exp_f32_e32 v101, v101
	v_add_f32_e32 v100, 1.0, v100
	v_add_f32_e32 v101, 1.0, v101
	v_rcp_f32_e32 v100, v100
	v_rcp_f32_e32 v101, v101
	v_mul_f32_e32 v87, v87, v100
	v_mul_f32_e32 v83, v83, v101
	v_mul_f32_e32 v87, v87, v91
	v_mul_f32_e32 v83, v83, v95
	v_cndmask_b32_e64 v87, v87, v100, s[6:7]
	v_cndmask_b32_e64 v83, v83, v101, s[6:7]
	v_mul_f32_e32 v100, 0xbfb8aa3b, v88
	v_mul_f32_e32 v101, 0xbfb8aa3b, v84
	v_exp_f32_e32 v100, v100
	v_exp_f32_e32 v101, v101
	v_add_f32_e32 v100, 1.0, v100
	v_add_f32_e32 v101, 1.0, v101
	v_rcp_f32_e32 v100, v100
	v_rcp_f32_e32 v101, v101
	v_mul_f32_e32 v88, v88, v100
	v_mul_f32_e32 v84, v84, v101
	v_mul_f32_e32 v88, v88, v92
	v_mul_f32_e32 v84, v84, v96
	v_cndmask_b32_e64 v88, v88, v100, s[6:7]
	v_cndmask_b32_e64 v84, v84, v101, s[6:7]
	v_mul_f32_e32 v100, 0xbfb8aa3b, v89
	v_mul_f32_e32 v101, 0xbfb8aa3b, v85
	v_exp_f32_e32 v100, v100
	v_exp_f32_e32 v101, v101
	v_add_f32_e32 v100, 1.0, v100
	v_add_f32_e32 v101, 1.0, v101
	v_rcp_f32_e32 v100, v100
	v_rcp_f32_e32 v101, v101
	v_mul_f32_e32 v89, v89, v100
	v_mul_f32_e32 v85, v85, v101
	v_mul_f32_e32 v89, v89, v93
	v_mul_f32_e32 v85, v85, v97
	v_cndmask_b32_e64 v89, v89, v100, s[6:7]
	v_cndmask_b32_e64 v85, v85, v101, s[6:7]
.LBB0_289:
	v_cvt_pk_bf16_f32 v86, v86, v87
	v_cvt_pk_bf16_f32 v87, v88, v89
	v_cvt_pk_bf16_f32 v88, v82, v83
	v_cvt_pk_bf16_f32 v89, v84, v85
	global_store_dwordx4 v[98:99], v[86:89], off offset:256 nt
	s_and_b64 vcc, exec, s[8:9]
	v_mov_b32_e32 v84, v14
	v_mov_b32_e32 v86, v15
	v_mov_b32_e32 v88, v16
	v_mov_b32_e32 v98, v17
	v_mov_b32_e32 v85, v10
	v_mov_b32_e32 v87, v11
	v_mov_b32_e32 v89, v12
	v_mov_b32_e32 v99, v13
	s_cbranch_vccnz .LBB0_291
	v_mul_f32_e32 v82, 0xbfb8aa3b, v14
	v_exp_f32_e32 v82, v82
	v_mul_f32_e32 v83, 0xbfb8aa3b, v10
	v_exp_f32_e32 v83, v83
	v_mul_f32_e32 v85, 0xbfb8aa3b, v15
	v_add_f32_e32 v82, 1.0, v82
	v_rcp_f32_e32 v82, v82
	v_add_f32_e32 v83, 1.0, v83
	v_rcp_f32_e32 v83, v83
	v_mul_f32_e32 v87, 0xbfb8aa3b, v16
	v_mul_f32_e32 v84, v14, v82
	v_mul_f32_e32 v84, v84, v90
	v_mul_f32_e32 v86, v10, v83
	v_cndmask_b32_e64 v84, v84, v82, s[6:7]
	v_exp_f32_e32 v82, v85
	v_mul_f32_e32 v85, v86, v94
	v_mul_f32_e32 v86, 0xbfb8aa3b, v11
	v_exp_f32_e32 v86, v86
	v_add_f32_e32 v82, 1.0, v82
	v_exp_f32_e32 v87, v87
	v_rcp_f32_e32 v82, v82
	v_cndmask_b32_e64 v85, v85, v83, s[6:7]
	v_add_f32_e32 v83, 1.0, v86
	v_rcp_f32_e32 v83, v83
	v_add_f32_e32 v87, 1.0, v87
	v_mul_f32_e32 v86, v15, v82
	v_rcp_f32_e32 v89, v87
	v_mul_f32_e32 v86, v86, v91
	v_mul_f32_e32 v88, 0xbfb8aa3b, v12
	v_cndmask_b32_e64 v86, v86, v82, s[6:7]
	v_mul_f32_e32 v82, v11, v83
	v_exp_f32_e32 v88, v88
	v_mul_f32_e32 v82, v82, v95
	v_cndmask_b32_e64 v87, v82, v83, s[6:7]
	v_mul_f32_e32 v83, v16, v89
	v_mul_f32_e32 v83, v83, v92
	v_add_f32_e32 v82, 1.0, v88
	v_cndmask_b32_e64 v88, v83, v89, s[6:7]
	v_mul_f32_e32 v89, 0xbfb8aa3b, v17
	v_rcp_f32_e32 v82, v82
	v_exp_f32_e32 v89, v89
	v_mul_f32_e32 v98, 0xbfb8aa3b, v13
	v_exp_f32_e32 v98, v98
	v_mul_f32_e32 v83, v12, v82
	v_add_f32_e32 v89, 1.0, v89
	v_mul_f32_e32 v83, v83, v96
	v_rcp_f32_e32 v99, v89
	v_cndmask_b32_e64 v89, v83, v82, s[6:7]
	v_add_f32_e32 v82, 1.0, v98
	v_rcp_f32_e32 v82, v82
	v_mul_f32_e32 v83, v17, v99
	v_mul_f32_e32 v83, v83, v93
	v_cndmask_b32_e64 v98, v83, v99, s[6:7]
	v_mul_f32_e32 v83, v13, v82
	v_mul_f32_e32 v83, v83, v97
	v_cndmask_b32_e64 v99, v83, v82, s[6:7]
.LBB0_291:
	v_readlane_b32 s38, v249, 43
	v_readlane_b32 s39, v249, 44
	v_add_u32_e32 v100, 0xa0, v152
	s_and_b64 vcc, exec, s[8:9]
	v_mov_b64_e32 v[82:83], s[38:39]
	v_mad_i64_i32 v[82:83], s[38:39], v100, s76, v[82:83]
	v_lshl_add_u64 v[82:83], v[154:155], 1, v[82:83]
	v_cvt_pk_bf16_f32 v100, v84, v86
	v_cvt_pk_bf16_f32 v101, v88, v98
	v_cvt_pk_bf16_f32 v102, v85, v87
	v_cvt_pk_bf16_f32 v103, v89, v99
	global_store_dwordx4 v[82:83], v[100:103], off nt
	s_cbranch_vccnz .LBB0_293
	v_mul_f32_e32 v84, 0xbfb8aa3b, v78
	v_mul_f32_e32 v85, 0xbfb8aa3b, v74
	v_exp_f32_e32 v84, v84
	v_exp_f32_e32 v85, v85
	v_add_f32_e32 v84, 1.0, v84
	v_add_f32_e32 v85, 1.0, v85
	v_rcp_f32_e32 v84, v84
	v_rcp_f32_e32 v85, v85
	v_mul_f32_e32 v78, v78, v84
	v_mul_f32_e32 v74, v74, v85
	v_mul_f32_e32 v78, v78, v90
	v_mul_f32_e32 v74, v74, v94
	v_cndmask_b32_e64 v78, v78, v84, s[6:7]
	v_cndmask_b32_e64 v74, v74, v85, s[6:7]
	v_mul_f32_e32 v84, 0xbfb8aa3b, v79
	v_mul_f32_e32 v85, 0xbfb8aa3b, v75
	v_exp_f32_e32 v84, v84
	v_exp_f32_e32 v85, v85
	v_add_f32_e32 v84, 1.0, v84
	v_add_f32_e32 v85, 1.0, v85
	v_rcp_f32_e32 v84, v84
	v_rcp_f32_e32 v85, v85
	v_mul_f32_e32 v79, v79, v84
	v_mul_f32_e32 v75, v75, v85
	v_mul_f32_e32 v79, v79, v91
	v_mul_f32_e32 v75, v75, v95
	v_cndmask_b32_e64 v79, v79, v84, s[6:7]
	v_cndmask_b32_e64 v75, v75, v85, s[6:7]
	v_mul_f32_e32 v84, 0xbfb8aa3b, v80
	v_mul_f32_e32 v85, 0xbfb8aa3b, v76
	v_exp_f32_e32 v84, v84
	v_exp_f32_e32 v85, v85
	v_add_f32_e32 v84, 1.0, v84
	v_add_f32_e32 v85, 1.0, v85
	v_rcp_f32_e32 v84, v84
	v_rcp_f32_e32 v85, v85
	v_mul_f32_e32 v80, v80, v84
	v_mul_f32_e32 v76, v76, v85
	v_mul_f32_e32 v80, v80, v92
	v_mul_f32_e32 v76, v76, v96
	v_cndmask_b32_e64 v80, v80, v84, s[6:7]
	v_cndmask_b32_e64 v76, v76, v85, s[6:7]
	v_mul_f32_e32 v84, 0xbfb8aa3b, v81
	v_mul_f32_e32 v85, 0xbfb8aa3b, v77
	v_exp_f32_e32 v84, v84
	v_exp_f32_e32 v85, v85
	v_add_f32_e32 v84, 1.0, v84
	v_add_f32_e32 v85, 1.0, v85
	v_rcp_f32_e32 v84, v84
	v_rcp_f32_e32 v85, v85
	v_mul_f32_e32 v81, v81, v84
	v_mul_f32_e32 v77, v77, v85
	v_mul_f32_e32 v81, v81, v93
	v_mul_f32_e32 v77, v77, v97
	v_cndmask_b32_e64 v81, v81, v84, s[6:7]
	v_cndmask_b32_e64 v77, v77, v85, s[6:7]
.LBB0_293:
	v_cvt_pk_bf16_f32 v78, v78, v79
	v_cvt_pk_bf16_f32 v79, v80, v81
	v_cvt_pk_bf16_f32 v80, v74, v75
	v_cvt_pk_bf16_f32 v81, v76, v77
	global_store_dwordx4 v[82:83], v[78:81], off offset:256 nt
	s_and_b64 vcc, exec, s[8:9]
	v_mov_b32_e32 v76, v6
	v_mov_b32_e32 v78, v7
	v_mov_b32_e32 v80, v8
	v_mov_b32_e32 v82, v9
	v_mov_b32_e32 v77, v2
	v_mov_b32_e32 v79, v3
	v_mov_b32_e32 v81, v4
	v_mov_b32_e32 v83, v5
	s_cbranch_vccnz .LBB0_295
	v_mul_f32_e32 v74, 0xbfb8aa3b, v6
	v_exp_f32_e32 v74, v74
	v_mul_f32_e32 v75, 0xbfb8aa3b, v2
	v_exp_f32_e32 v75, v75
	v_mul_f32_e32 v77, 0xbfb8aa3b, v7
	v_add_f32_e32 v74, 1.0, v74
	v_rcp_f32_e32 v74, v74
	v_add_f32_e32 v75, 1.0, v75
	v_rcp_f32_e32 v75, v75
	v_mul_f32_e32 v79, 0xbfb8aa3b, v8
	v_mul_f32_e32 v76, v6, v74
	v_mul_f32_e32 v76, v76, v90
	v_mul_f32_e32 v78, v2, v75
	v_cndmask_b32_e64 v76, v76, v74, s[6:7]
	v_exp_f32_e32 v74, v77
	v_mul_f32_e32 v77, v78, v94
	v_mul_f32_e32 v78, 0xbfb8aa3b, v3
	v_exp_f32_e32 v78, v78
	v_add_f32_e32 v74, 1.0, v74
	v_exp_f32_e32 v79, v79
	v_rcp_f32_e32 v74, v74
	v_cndmask_b32_e64 v77, v77, v75, s[6:7]
	v_add_f32_e32 v75, 1.0, v78
	v_rcp_f32_e32 v75, v75
	v_add_f32_e32 v79, 1.0, v79
	v_mul_f32_e32 v78, v7, v74
	v_rcp_f32_e32 v81, v79
	v_mul_f32_e32 v78, v78, v91
	v_mul_f32_e32 v80, 0xbfb8aa3b, v4
	v_cndmask_b32_e64 v78, v78, v74, s[6:7]
	v_mul_f32_e32 v74, v3, v75
	v_exp_f32_e32 v80, v80
	v_mul_f32_e32 v74, v74, v95
	v_cndmask_b32_e64 v79, v74, v75, s[6:7]
	v_mul_f32_e32 v75, v8, v81
	v_mul_f32_e32 v75, v75, v92
	v_add_f32_e32 v74, 1.0, v80
	v_cndmask_b32_e64 v80, v75, v81, s[6:7]
	v_mul_f32_e32 v81, 0xbfb8aa3b, v9
	v_rcp_f32_e32 v74, v74
	v_exp_f32_e32 v81, v81
	v_mul_f32_e32 v82, 0xbfb8aa3b, v5
	v_exp_f32_e32 v82, v82
	v_mul_f32_e32 v75, v4, v74
	v_add_f32_e32 v81, 1.0, v81
	v_mul_f32_e32 v75, v75, v96
	v_rcp_f32_e32 v83, v81
	v_cndmask_b32_e64 v81, v75, v74, s[6:7]
	v_add_f32_e32 v74, 1.0, v82
	v_rcp_f32_e32 v74, v74
	v_mul_f32_e32 v75, v9, v83
	v_mul_f32_e32 v75, v75, v93
	v_cndmask_b32_e64 v82, v75, v83, s[6:7]
	v_mul_f32_e32 v75, v5, v74
	v_mul_f32_e32 v75, v75, v97
	v_cndmask_b32_e64 v83, v75, v74, s[6:7]
.LBB0_295:
	v_readlane_b32 s38, v249, 43
	v_readlane_b32 s39, v249, 44
	v_add_u32_e32 v84, 0xb0, v152
	s_and_b64 vcc, exec, s[8:9]
	v_mov_b64_e32 v[74:75], s[38:39]
	v_mad_i64_i32 v[74:75], s[38:39], v84, s76, v[74:75]
	v_lshl_add_u64 v[74:75], v[154:155], 1, v[74:75]
	v_cvt_pk_bf16_f32 v84, v76, v78
	v_cvt_pk_bf16_f32 v85, v80, v82
	v_cvt_pk_bf16_f32 v86, v77, v79
	v_cvt_pk_bf16_f32 v87, v81, v83
	global_store_dwordx4 v[74:75], v[84:87], off nt
	s_cbranch_vccnz .LBB0_297
	v_mul_f32_e32 v76, 0xbfb8aa3b, v38
	v_mul_f32_e32 v77, 0xbfb8aa3b, v30
	v_exp_f32_e32 v76, v76
	v_exp_f32_e32 v77, v77
	v_add_f32_e32 v76, 1.0, v76
	v_add_f32_e32 v77, 1.0, v77
	v_rcp_f32_e32 v76, v76
	v_rcp_f32_e32 v77, v77
	v_mul_f32_e32 v38, v38, v76
	v_mul_f32_e32 v30, v30, v77
	v_mul_f32_e32 v38, v38, v90
	v_mul_f32_e32 v30, v30, v94
	v_cndmask_b32_e64 v38, v38, v76, s[6:7]
	v_cndmask_b32_e64 v30, v30, v77, s[6:7]
	v_mul_f32_e32 v76, 0xbfb8aa3b, v39
	v_mul_f32_e32 v77, 0xbfb8aa3b, v31
	v_exp_f32_e32 v76, v76
	v_exp_f32_e32 v77, v77
	v_add_f32_e32 v76, 1.0, v76
	v_add_f32_e32 v77, 1.0, v77
	v_rcp_f32_e32 v76, v76
	v_rcp_f32_e32 v77, v77
	v_mul_f32_e32 v39, v39, v76
	v_mul_f32_e32 v31, v31, v77
	v_mul_f32_e32 v39, v39, v91
	v_mul_f32_e32 v31, v31, v95
	v_cndmask_b32_e64 v39, v39, v76, s[6:7]
	v_cndmask_b32_e64 v31, v31, v77, s[6:7]
	v_mul_f32_e32 v76, 0xbfb8aa3b, v40
	v_mul_f32_e32 v77, 0xbfb8aa3b, v32
	v_exp_f32_e32 v76, v76
	v_exp_f32_e32 v77, v77
	v_add_f32_e32 v76, 1.0, v76
	v_add_f32_e32 v77, 1.0, v77
	v_rcp_f32_e32 v76, v76
	v_rcp_f32_e32 v77, v77
	v_mul_f32_e32 v40, v40, v76
	v_mul_f32_e32 v32, v32, v77
	v_mul_f32_e32 v40, v40, v92
	v_mul_f32_e32 v32, v32, v96
	v_cndmask_b32_e64 v40, v40, v76, s[6:7]
	v_cndmask_b32_e64 v32, v32, v77, s[6:7]
	v_mul_f32_e32 v76, 0xbfb8aa3b, v41
	v_mul_f32_e32 v77, 0xbfb8aa3b, v33
	v_exp_f32_e32 v76, v76
	v_exp_f32_e32 v77, v77
	v_add_f32_e32 v76, 1.0, v76
	v_add_f32_e32 v77, 1.0, v77
	v_rcp_f32_e32 v76, v76
	v_rcp_f32_e32 v77, v77
	v_mul_f32_e32 v41, v41, v76
	v_mul_f32_e32 v33, v33, v77
	v_mul_f32_e32 v41, v41, v93
	v_mul_f32_e32 v33, v33, v97
	v_cndmask_b32_e64 v41, v41, v76, s[6:7]
	v_cndmask_b32_e64 v33, v33, v77, s[6:7]

.LBB0_720:
	v_lshl_or_b32 v158, s4, 8, v167
	v_mov_b64_e32 v[160:161], s[64:65]
	v_ashrrev_i32_e32 v159, 31, v158
	v_mad_i64_i32 v[160:161], s[4:5], v156, s49, v[160:161]
	v_cvt_pk_bf16_f32 v178, v157, v172
	v_cndmask_b32_e64 v157, 0, 1, s[26:27]
	v_lshl_add_u64 v[160:161], v[158:159], 1, v[160:161]
	v_cmp_ne_u32_e64 s[4:5], 1, v157
	s_andn2_b64 vcc, exec, s[26:27]
	v_cvt_pk_bf16_f32 v179, v174, v176
	v_cvt_pk_bf16_f32 v180, v171, v173
	v_cvt_pk_bf16_f32 v181, v175, v177
	global_store_dwordx4 v[160:161], v[178:181], off nt
	s_cbranch_vccnz .LBB0_722
	v_mul_f32_e32 v157, 0xbfb8aa3b, v134
	v_exp_f32_e32 v157, v157
	v_mul_f32_e32 v172, 0xbfb8aa3b, v135
	v_mul_f32_e32 v171, 0xbfb8aa3b, v130
	v_exp_f32_e32 v171, v171
	v_add_f32_e32 v157, 1.0, v157
	v_rcp_f32_e32 v157, v157
	v_add_f32_e32 v171, 1.0, v171
	v_rcp_f32_e32 v171, v171
	v_mul_f32_e32 v134, v134, v157
	v_mul_f32_e32 v134, v134, v98
	v_cndmask_b32_e64 v134, v134, v157, s[6:7]
	v_exp_f32_e32 v157, v172
	v_mul_f32_e32 v172, 0xbfb8aa3b, v131
	v_exp_f32_e32 v172, v172
	v_mul_f32_e32 v130, v130, v171
	v_add_f32_e32 v157, 1.0, v157
	v_rcp_f32_e32 v157, v157
	v_mul_f32_e32 v130, v130, v102
	v_cndmask_b32_e64 v130, v130, v171, s[6:7]
	v_add_f32_e32 v171, 1.0, v172
	v_mul_f32_e32 v135, v135, v157
	v_mul_f32_e32 v135, v135, v99
	v_cndmask_b32_e64 v135, v135, v157, s[6:7]
	v_mul_f32_e32 v157, 0xbfb8aa3b, v136
	v_exp_f32_e32 v157, v157
	v_rcp_f32_e32 v171, v171
	v_mul_f32_e32 v172, 0xbfb8aa3b, v132
	v_exp_f32_e32 v172, v172
	v_add_f32_e32 v157, 1.0, v157
	v_rcp_f32_e32 v157, v157
	v_mul_f32_e32 v131, v131, v171
	v_mul_f32_e32 v131, v131, v103
	v_cndmask_b32_e64 v131, v131, v171, s[6:7]
	v_add_f32_e32 v171, 1.0, v172
	v_mul_f32_e32 v136, v136, v157
	v_rcp_f32_e32 v171, v171
	v_mul_f32_e32 v136, v136, v100
	v_cndmask_b32_e64 v136, v136, v157, s[6:7]
	v_mul_f32_e32 v157, 0xbfb8aa3b, v137
	v_mul_f32_e32 v172, 0xbfb8aa3b, v133
	v_exp_f32_e32 v157, v157
	v_exp_f32_e32 v172, v172
	v_mul_f32_e32 v132, v132, v171
	v_mul_f32_e32 v132, v132, v104
	v_add_f32_e32 v157, 1.0, v157
	v_cndmask_b32_e64 v132, v132, v171, s[6:7]
	v_add_f32_e32 v171, 1.0, v172
	v_rcp_f32_e32 v157, v157
	v_rcp_f32_e32 v171, v171
	v_mul_f32_e32 v137, v137, v157
	v_mul_f32_e32 v133, v133, v171
	v_mul_f32_e32 v137, v137, v101
	v_mul_f32_e32 v133, v133, v105
	v_cndmask_b32_e64 v137, v137, v157, s[6:7]
	v_cndmask_b32_e64 v133, v133, v171, s[6:7]
.LBB0_722:
	v_cvt_pk_bf16_f32 v134, v134, v135
	v_cvt_pk_bf16_f32 v135, v136, v137
	v_cvt_pk_bf16_f32 v136, v130, v131
	v_cvt_pk_bf16_f32 v137, v132, v133
	global_store_dwordx4 v[160:161], v[134:137], off offset:256 nt
	s_and_b64 vcc, exec, s[4:5]
	v_mov_b32_e32 v132, v62
	v_mov_b32_e32 v134, v63
	v_mov_b32_e32 v136, v64
	v_mov_b32_e32 v157, v65
	v_mov_b32_e32 v133, v58
	v_mov_b32_e32 v135, v59
	v_mov_b32_e32 v137, v60
	v_mov_b32_e32 v160, v61
	s_cbranch_vccnz .LBB0_724
	v_mul_f32_e32 v130, 0xbfb8aa3b, v62
	v_exp_f32_e32 v130, v130
	v_mul_f32_e32 v131, 0xbfb8aa3b, v58
	v_exp_f32_e32 v131, v131
	v_mul_f32_e32 v133, 0xbfb8aa3b, v63
	v_add_f32_e32 v130, 1.0, v130
	v_rcp_f32_e32 v130, v130
	v_add_f32_e32 v131, 1.0, v131
	v_rcp_f32_e32 v131, v131
	v_mul_f32_e32 v135, 0xbfb8aa3b, v64
	v_mul_f32_e32 v132, v62, v130
	v_mul_f32_e32 v132, v132, v98
	v_mul_f32_e32 v134, v58, v131
	v_cndmask_b32_e64 v132, v132, v130, s[6:7]
	v_exp_f32_e32 v130, v133
	v_mul_f32_e32 v133, v134, v102
	v_mul_f32_e32 v134, 0xbfb8aa3b, v59
	v_exp_f32_e32 v134, v134
	v_add_f32_e32 v130, 1.0, v130
	v_exp_f32_e32 v135, v135
	v_rcp_f32_e32 v130, v130
	v_cndmask_b32_e64 v133, v133, v131, s[6:7]
	v_add_f32_e32 v131, 1.0, v134
	v_rcp_f32_e32 v131, v131
	v_add_f32_e32 v135, 1.0, v135
	v_mul_f32_e32 v134, v63, v130
	v_rcp_f32_e32 v137, v135
	v_mul_f32_e32 v134, v134, v99
	v_mul_f32_e32 v136, 0xbfb8aa3b, v60
	v_cndmask_b32_e64 v134, v134, v130, s[6:7]
	v_mul_f32_e32 v130, v59, v131
	v_exp_f32_e32 v136, v136
	v_mul_f32_e32 v130, v130, v103
	v_cndmask_b32_e64 v135, v130, v131, s[6:7]
	v_mul_f32_e32 v131, v64, v137
	v_mul_f32_e32 v131, v131, v100
	v_add_f32_e32 v130, 1.0, v136
	v_cndmask_b32_e64 v136, v131, v137, s[6:7]
	v_mul_f32_e32 v137, 0xbfb8aa3b, v65
	v_rcp_f32_e32 v130, v130
	v_exp_f32_e32 v137, v137
	v_mul_f32_e32 v157, 0xbfb8aa3b, v61
	v_exp_f32_e32 v157, v157
	v_mul_f32_e32 v131, v60, v130
	v_add_f32_e32 v137, 1.0, v137
	v_mul_f32_e32 v131, v131, v104
	v_rcp_f32_e32 v160, v137
	v_cndmask_b32_e64 v137, v131, v130, s[6:7]
	v_add_f32_e32 v130, 1.0, v157
	v_rcp_f32_e32 v130, v130
	v_mul_f32_e32 v131, v65, v160
	v_mul_f32_e32 v131, v131, v101
	v_cndmask_b32_e64 v157, v131, v160, s[6:7]
	v_mul_f32_e32 v131, v61, v130
	v_mul_f32_e32 v131, v131, v105
	v_cndmask_b32_e64 v160, v131, v130, s[6:7]
.LBB0_724:
	v_or_b32_e32 v161, 16, v156
	v_mov_b64_e32 v[130:131], s[64:65]
	v_mad_i64_i32 v[130:131], s[26:27], v161, s49, v[130:131]
	v_lshl_add_u64 v[130:131], v[158:159], 1, v[130:131]
	s_and_b64 vcc, exec, s[4:5]
	v_cvt_pk_bf16_f32 v172, v132, v134
	v_cvt_pk_bf16_f32 v173, v136, v157
	v_cvt_pk_bf16_f32 v174, v133, v135
	v_cvt_pk_bf16_f32 v175, v137, v160
	global_store_dwordx4 v[130:131], v[172:175], off nt
	s_cbranch_vccnz .LBB0_726
	v_mul_f32_e32 v132, 0xbfb8aa3b, v126
	v_exp_f32_e32 v132, v132
	v_mul_f32_e32 v134, 0xbfb8aa3b, v127
	v_mul_f32_e32 v133, 0xbfb8aa3b, v122
	v_exp_f32_e32 v133, v133
	v_add_f32_e32 v132, 1.0, v132
	v_rcp_f32_e32 v132, v132
	v_add_f32_e32 v133, 1.0, v133
	v_rcp_f32_e32 v133, v133
	v_mul_f32_e32 v126, v126, v132
	v_mul_f32_e32 v126, v126, v98
	v_cndmask_b32_e64 v126, v126, v132, s[6:7]
	v_exp_f32_e32 v132, v134
	v_mul_f32_e32 v134, 0xbfb8aa3b, v123
	v_exp_f32_e32 v134, v134
	v_mul_f32_e32 v122, v122, v133
	v_add_f32_e32 v132, 1.0, v132
	v_rcp_f32_e32 v132, v132
	v_mul_f32_e32 v122, v122, v102
	v_cndmask_b32_e64 v122, v122, v133, s[6:7]
	v_add_f32_e32 v133, 1.0, v134
	v_mul_f32_e32 v127, v127, v132
	v_mul_f32_e32 v127, v127, v99
	v_cndmask_b32_e64 v127, v127, v132, s[6:7]
	v_mul_f32_e32 v132, 0xbfb8aa3b, v128
	v_exp_f32_e32 v132, v132
	v_rcp_f32_e32 v133, v133
	v_mul_f32_e32 v134, 0xbfb8aa3b, v124
	v_exp_f32_e32 v134, v134
	v_add_f32_e32 v132, 1.0, v132
	v_rcp_f32_e32 v132, v132
	v_mul_f32_e32 v123, v123, v133
	v_mul_f32_e32 v123, v123, v103
	v_cndmask_b32_e64 v123, v123, v133, s[6:7]
	v_add_f32_e32 v133, 1.0, v134
	v_mul_f32_e32 v128, v128, v132
	v_rcp_f32_e32 v133, v133
	v_mul_f32_e32 v128, v128, v100
	v_cndmask_b32_e64 v128, v128, v132, s[6:7]
	v_mul_f32_e32 v132, 0xbfb8aa3b, v129
	v_mul_f32_e32 v134, 0xbfb8aa3b, v125
	v_exp_f32_e32 v132, v132
	v_exp_f32_e32 v134, v134
	v_mul_f32_e32 v124, v124, v133
	v_mul_f32_e32 v124, v124, v104
	v_add_f32_e32 v132, 1.0, v132
	v_cndmask_b32_e64 v124, v124, v133, s[6:7]
	v_add_f32_e32 v133, 1.0, v134
	v_rcp_f32_e32 v132, v132
	v_rcp_f32_e32 v133, v133
	v_mul_f32_e32 v129, v129, v132
	v_mul_f32_e32 v125, v125, v133
	v_mul_f32_e32 v129, v129, v101
	v_mul_f32_e32 v125, v125, v105
	v_cndmask_b32_e64 v129, v129, v132, s[6:7]
	v_cndmask_b32_e64 v125, v125, v133, s[6:7]
.LBB0_726:
	v_cvt_pk_bf16_f32 v126, v126, v127
	v_cvt_pk_bf16_f32 v127, v128, v129
	v_cvt_pk_bf16_f32 v128, v122, v123
	v_cvt_pk_bf16_f32 v129, v124, v125
	global_store_dwordx4 v[130:131], v[126:129], off offset:256 nt
	s_and_b64 vcc, exec, s[4:5]
	v_mov_b32_e32 v124, v54
	v_mov_b32_e32 v126, v55
	v_mov_b32_e32 v128, v56
	v_mov_b32_e32 v130, v57
	v_mov_b32_e32 v125, v50
	v_mov_b32_e32 v127, v51
	v_mov_b32_e32 v129, v52
	v_mov_b32_e32 v131, v53
	s_cbranch_vccnz .LBB0_728
	v_mul_f32_e32 v122, 0xbfb8aa3b, v54
	v_exp_f32_e32 v122, v122
	v_mul_f32_e32 v123, 0xbfb8aa3b, v50
	v_exp_f32_e32 v123, v123
	v_mul_f32_e32 v125, 0xbfb8aa3b, v55
	v_add_f32_e32 v122, 1.0, v122
	v_rcp_f32_e32 v122, v122
	v_add_f32_e32 v123, 1.0, v123
	v_rcp_f32_e32 v123, v123
	v_mul_f32_e32 v127, 0xbfb8aa3b, v56
	v_mul_f32_e32 v124, v54, v122
	v_mul_f32_e32 v124, v124, v98
	v_mul_f32_e32 v126, v50, v123
	v_cndmask_b32_e64 v124, v124, v122, s[6:7]
	v_exp_f32_e32 v122, v125
	v_mul_f32_e32 v125, v126, v102
	v_mul_f32_e32 v126, 0xbfb8aa3b, v51
	v_exp_f32_e32 v126, v126
	v_add_f32_e32 v122, 1.0, v122
	v_exp_f32_e32 v127, v127
	v_rcp_f32_e32 v122, v122
	v_cndmask_b32_e64 v125, v125, v123, s[6:7]
	v_add_f32_e32 v123, 1.0, v126
	v_rcp_f32_e32 v123, v123
	v_add_f32_e32 v127, 1.0, v127
	v_mul_f32_e32 v126, v55, v122
	v_rcp_f32_e32 v129, v127
	v_mul_f32_e32 v126, v126, v99
	v_mul_f32_e32 v128, 0xbfb8aa3b, v52
	v_cndmask_b32_e64 v126, v126, v122, s[6:7]
	v_mul_f32_e32 v122, v51, v123
	v_exp_f32_e32 v128, v128
	v_mul_f32_e32 v122, v122, v103
	v_cndmask_b32_e64 v127, v122, v123, s[6:7]
	v_mul_f32_e32 v123, v56, v129
	v_mul_f32_e32 v123, v123, v100
	v_add_f32_e32 v122, 1.0, v128
	v_cndmask_b32_e64 v128, v123, v129, s[6:7]
	v_mul_f32_e32 v129, 0xbfb8aa3b, v57
	v_rcp_f32_e32 v122, v122
	v_exp_f32_e32 v129, v129
	v_mul_f32_e32 v130, 0xbfb8aa3b, v53
	v_exp_f32_e32 v130, v130
	v_mul_f32_e32 v123, v52, v122
	v_add_f32_e32 v129, 1.0, v129
	v_mul_f32_e32 v123, v123, v104
	v_rcp_f32_e32 v131, v129
	v_cndmask_b32_e64 v129, v123, v122, s[6:7]
	v_add_f32_e32 v122, 1.0, v130
	v_rcp_f32_e32 v122, v122
	v_mul_f32_e32 v123, v57, v131
	v_mul_f32_e32 v123, v123, v101
	v_cndmask_b32_e64 v130, v123, v131, s[6:7]
	v_mul_f32_e32 v123, v53, v122
	v_mul_f32_e32 v123, v123, v105
	v_cndmask_b32_e64 v131, v123, v122, s[6:7]
.LBB0_728:
	v_or_b32_e32 v132, 32, v156
	v_mov_b64_e32 v[122:123], s[64:65]
	v_mad_i64_i32 v[122:123], s[26:27], v132, s49, v[122:123]
	v_lshl_add_u64 v[122:123], v[158:159], 1, v[122:123]
	s_and_b64 vcc, exec, s[4:5]
	v_cvt_pk_bf16_f32 v132, v124, v126
	v_cvt_pk_bf16_f32 v133, v128, v130
	v_cvt_pk_bf16_f32 v134, v125, v127
	v_cvt_pk_bf16_f32 v135, v129, v131
	global_store_dwordx4 v[122:123], v[132:135], off nt
	s_cbranch_vccnz .LBB0_730
	v_mul_f32_e32 v124, 0xbfb8aa3b, v118
	v_exp_f32_e32 v124, v124
	v_mul_f32_e32 v126, 0xbfb8aa3b, v119
	v_mul_f32_e32 v125, 0xbfb8aa3b, v114
	v_exp_f32_e32 v125, v125
	v_add_f32_e32 v124, 1.0, v124
	v_rcp_f32_e32 v124, v124
	v_add_f32_e32 v125, 1.0, v125
	v_rcp_f32_e32 v125, v125
	v_mul_f32_e32 v118, v118, v124
	v_mul_f32_e32 v118, v118, v98
	v_cndmask_b32_e64 v118, v118, v124, s[6:7]
	v_exp_f32_e32 v124, v126
	v_mul_f32_e32 v126, 0xbfb8aa3b, v115
	v_exp_f32_e32 v126, v126
	v_mul_f32_e32 v114, v114, v125
	v_add_f32_e32 v124, 1.0, v124
	v_rcp_f32_e32 v124, v124
	v_mul_f32_e32 v114, v114, v102
	v_cndmask_b32_e64 v114, v114, v125, s[6:7]
	v_add_f32_e32 v125, 1.0, v126
	v_mul_f32_e32 v119, v119, v124
	v_mul_f32_e32 v119, v119, v99
	v_cndmask_b32_e64 v119, v119, v124, s[6:7]
	v_mul_f32_e32 v124, 0xbfb8aa3b, v120
	v_exp_f32_e32 v124, v124
	v_rcp_f32_e32 v125, v125
	v_mul_f32_e32 v126, 0xbfb8aa3b, v116
	v_exp_f32_e32 v126, v126
	v_add_f32_e32 v124, 1.0, v124
	v_rcp_f32_e32 v124, v124
	v_mul_f32_e32 v115, v115, v125
	v_mul_f32_e32 v115, v115, v103
	v_cndmask_b32_e64 v115, v115, v125, s[6:7]
	v_add_f32_e32 v125, 1.0, v126
	v_mul_f32_e32 v120, v120, v124
	v_rcp_f32_e32 v125, v125
	v_mul_f32_e32 v120, v120, v100
	v_cndmask_b32_e64 v120, v120, v124, s[6:7]
	v_mul_f32_e32 v124, 0xbfb8aa3b, v121
	v_mul_f32_e32 v126, 0xbfb8aa3b, v117
	v_exp_f32_e32 v124, v124
	v_exp_f32_e32 v126, v126
	v_mul_f32_e32 v116, v116, v125
	v_mul_f32_e32 v116, v116, v104
	v_add_f32_e32 v124, 1.0, v124
	v_cndmask_b32_e64 v116, v116, v125, s[6:7]
	v_add_f32_e32 v125, 1.0, v126
	v_rcp_f32_e32 v124, v124
	v_rcp_f32_e32 v125, v125
	v_mul_f32_e32 v121, v121, v124
	v_mul_f32_e32 v117, v117, v125
	v_mul_f32_e32 v121, v121, v101
	v_mul_f32_e32 v117, v117, v105
	v_cndmask_b32_e64 v121, v121, v124, s[6:7]
	v_cndmask_b32_e64 v117, v117, v125, s[6:7]
.LBB0_730:
	v_cvt_pk_bf16_f32 v118, v118, v119
	v_cvt_pk_bf16_f32 v119, v120, v121
	v_cvt_pk_bf16_f32 v120, v114, v115
	v_cvt_pk_bf16_f32 v121, v116, v117
	global_store_dwordx4 v[122:123], v[118:121], off offset:256 nt
	s_and_b64 vcc, exec, s[4:5]
	v_mov_b32_e32 v116, v46
	v_mov_b32_e32 v118, v47
	v_mov_b32_e32 v120, v48
	v_mov_b32_e32 v122, v49
	v_mov_b32_e32 v117, v42
	v_mov_b32_e32 v119, v43
	v_mov_b32_e32 v121, v44
	v_mov_b32_e32 v123, v45
	s_cbranch_vccnz .LBB0_732
	v_mul_f32_e32 v114, 0xbfb8aa3b, v46
	v_exp_f32_e32 v114, v114
	v_mul_f32_e32 v115, 0xbfb8aa3b, v42
	v_exp_f32_e32 v115, v115
	v_mul_f32_e32 v117, 0xbfb8aa3b, v47
	v_add_f32_e32 v114, 1.0, v114
	v_rcp_f32_e32 v114, v114
	v_add_f32_e32 v115, 1.0, v115
	v_rcp_f32_e32 v115, v115
	v_mul_f32_e32 v119, 0xbfb8aa3b, v48
	v_mul_f32_e32 v116, v46, v114
	v_mul_f32_e32 v116, v116, v98
	v_mul_f32_e32 v118, v42, v115
	v_cndmask_b32_e64 v116, v116, v114, s[6:7]
	v_exp_f32_e32 v114, v117
	v_mul_f32_e32 v117, v118, v102
	v_mul_f32_e32 v118, 0xbfb8aa3b, v43
	v_exp_f32_e32 v118, v118
	v_add_f32_e32 v114, 1.0, v114
	v_exp_f32_e32 v119, v119
	v_rcp_f32_e32 v114, v114
	v_cndmask_b32_e64 v117, v117, v115, s[6:7]
	v_add_f32_e32 v115, 1.0, v118
	v_rcp_f32_e32 v115, v115
	v_add_f32_e32 v119, 1.0, v119
	v_mul_f32_e32 v118, v47, v114
	v_rcp_f32_e32 v121, v119
	v_mul_f32_e32 v118, v118, v99
	v_mul_f32_e32 v120, 0xbfb8aa3b, v44
	v_cndmask_b32_e64 v118, v118, v114, s[6:7]
	v_mul_f32_e32 v114, v43, v115
	v_exp_f32_e32 v120, v120
	v_mul_f32_e32 v114, v114, v103
	v_cndmask_b32_e64 v119, v114, v115, s[6:7]
	v_mul_f32_e32 v115, v48, v121
	v_mul_f32_e32 v115, v115, v100
	v_add_f32_e32 v114, 1.0, v120
	v_cndmask_b32_e64 v120, v115, v121, s[6:7]
	v_mul_f32_e32 v121, 0xbfb8aa3b, v49
	v_rcp_f32_e32 v114, v114
	v_exp_f32_e32 v121, v121
	v_mul_f32_e32 v122, 0xbfb8aa3b, v45
	v_exp_f32_e32 v122, v122
	v_mul_f32_e32 v115, v44, v114
	v_add_f32_e32 v121, 1.0, v121
	v_mul_f32_e32 v115, v115, v104
	v_rcp_f32_e32 v123, v121
	v_cndmask_b32_e64 v121, v115, v114, s[6:7]
	v_add_f32_e32 v114, 1.0, v122
	v_rcp_f32_e32 v114, v114
	v_mul_f32_e32 v115, v49, v123
	v_mul_f32_e32 v115, v115, v101
	v_cndmask_b32_e64 v122, v115, v123, s[6:7]
	v_mul_f32_e32 v115, v45, v114
	v_mul_f32_e32 v115, v115, v105
	v_cndmask_b32_e64 v123, v115, v114, s[6:7]
.LBB0_732:
	v_or_b32_e32 v124, 48, v156
	v_mov_b64_e32 v[114:115], s[64:65]
	v_mad_i64_i32 v[114:115], s[26:27], v124, s49, v[114:115]
	v_lshl_add_u64 v[114:115], v[158:159], 1, v[114:115]
	s_and_b64 vcc, exec, s[4:5]
	v_cvt_pk_bf16_f32 v124, v116, v118
	v_cvt_pk_bf16_f32 v125, v120, v122
	v_cvt_pk_bf16_f32 v126, v117, v119
	v_cvt_pk_bf16_f32 v127, v121, v123
	global_store_dwordx4 v[114:115], v[124:127], off nt
	s_cbranch_vccnz .LBB0_734
	v_mul_f32_e32 v116, 0xbfb8aa3b, v110
	v_exp_f32_e32 v116, v116
	v_mul_f32_e32 v118, 0xbfb8aa3b, v111
	v_mul_f32_e32 v117, 0xbfb8aa3b, v106
	v_exp_f32_e32 v117, v117
	v_add_f32_e32 v116, 1.0, v116
	v_rcp_f32_e32 v116, v116
	v_add_f32_e32 v117, 1.0, v117
	v_rcp_f32_e32 v117, v117
	v_mul_f32_e32 v110, v110, v116
	v_mul_f32_e32 v110, v110, v98
	v_cndmask_b32_e64 v110, v110, v116, s[6:7]
	v_exp_f32_e32 v116, v118
	v_mul_f32_e32 v118, 0xbfb8aa3b, v107
	v_exp_f32_e32 v118, v118
	v_mul_f32_e32 v106, v106, v117
	v_add_f32_e32 v116, 1.0, v116
	v_rcp_f32_e32 v116, v116
	v_mul_f32_e32 v106, v106, v102
	v_cndmask_b32_e64 v106, v106, v117, s[6:7]
	v_add_f32_e32 v117, 1.0, v118
	v_mul_f32_e32 v111, v111, v116
	v_mul_f32_e32 v111, v111, v99
	v_cndmask_b32_e64 v111, v111, v116, s[6:7]
	v_mul_f32_e32 v116, 0xbfb8aa3b, v112
	v_exp_f32_e32 v116, v116
	v_rcp_f32_e32 v117, v117
	v_mul_f32_e32 v118, 0xbfb8aa3b, v108
	v_exp_f32_e32 v118, v118
	v_add_f32_e32 v116, 1.0, v116
	v_rcp_f32_e32 v116, v116
	v_mul_f32_e32 v107, v107, v117
	v_mul_f32_e32 v107, v107, v103
	v_cndmask_b32_e64 v107, v107, v117, s[6:7]
	v_add_f32_e32 v117, 1.0, v118
	v_mul_f32_e32 v112, v112, v116
	v_rcp_f32_e32 v117, v117
	v_mul_f32_e32 v112, v112, v100
	v_cndmask_b32_e64 v112, v112, v116, s[6:7]
	v_mul_f32_e32 v116, 0xbfb8aa3b, v113
	v_mul_f32_e32 v118, 0xbfb8aa3b, v109
	v_exp_f32_e32 v116, v116
	v_exp_f32_e32 v118, v118
	v_mul_f32_e32 v108, v108, v117
	v_mul_f32_e32 v108, v108, v104
	v_add_f32_e32 v116, 1.0, v116
	v_cndmask_b32_e64 v108, v108, v117, s[6:7]
	v_add_f32_e32 v117, 1.0, v118
	v_rcp_f32_e32 v116, v116
	v_rcp_f32_e32 v117, v117
	v_mul_f32_e32 v113, v113, v116
	v_mul_f32_e32 v109, v109, v117
	v_mul_f32_e32 v113, v113, v101
	v_mul_f32_e32 v109, v109, v105
	v_cndmask_b32_e64 v113, v113, v116, s[6:7]
	v_cndmask_b32_e64 v109, v109, v117, s[6:7]
.LBB0_734:
	v_cvt_pk_bf16_f32 v110, v110, v111
	v_cvt_pk_bf16_f32 v111, v112, v113
	v_cvt_pk_bf16_f32 v112, v106, v107
	v_cvt_pk_bf16_f32 v113, v108, v109
	global_store_dwordx4 v[114:115], v[110:113], off offset:256 nt
	s_and_b64 vcc, exec, s[4:5]
	v_mov_b32_e32 v108, v34
	v_mov_b32_e32 v110, v35
	v_mov_b32_e32 v112, v36
	v_mov_b32_e32 v114, v37
	v_mov_b32_e32 v109, v26
	v_mov_b32_e32 v111, v27
	v_mov_b32_e32 v113, v28
	v_mov_b32_e32 v115, v29
	s_cbranch_vccnz .LBB0_736
	v_mul_f32_e32 v106, 0xbfb8aa3b, v34
	v_exp_f32_e32 v106, v106
	v_mul_f32_e32 v107, 0xbfb8aa3b, v26
	v_exp_f32_e32 v107, v107
	v_mul_f32_e32 v109, 0xbfb8aa3b, v35
	v_add_f32_e32 v106, 1.0, v106
	v_rcp_f32_e32 v106, v106
	v_add_f32_e32 v107, 1.0, v107
	v_rcp_f32_e32 v107, v107
	v_mul_f32_e32 v111, 0xbfb8aa3b, v36
	v_mul_f32_e32 v108, v34, v106
	v_mul_f32_e32 v108, v108, v98
	v_mul_f32_e32 v110, v26, v107
	v_cndmask_b32_e64 v108, v108, v106, s[6:7]
	v_exp_f32_e32 v106, v109
	v_mul_f32_e32 v109, v110, v102
	v_mul_f32_e32 v110, 0xbfb8aa3b, v27
	v_exp_f32_e32 v110, v110
	v_add_f32_e32 v106, 1.0, v106
	v_exp_f32_e32 v111, v111
	v_rcp_f32_e32 v106, v106
	v_cndmask_b32_e64 v109, v109, v107, s[6:7]
	v_add_f32_e32 v107, 1.0, v110
	v_rcp_f32_e32 v107, v107
	v_add_f32_e32 v111, 1.0, v111
	v_mul_f32_e32 v110, v35, v106
	v_rcp_f32_e32 v113, v111
	v_mul_f32_e32 v110, v110, v99
	v_mul_f32_e32 v112, 0xbfb8aa3b, v28
	v_cndmask_b32_e64 v110, v110, v106, s[6:7]
	v_mul_f32_e32 v106, v27, v107
	v_exp_f32_e32 v112, v112
	v_mul_f32_e32 v106, v106, v103
	v_cndmask_b32_e64 v111, v106, v107, s[6:7]
	v_mul_f32_e32 v107, v36, v113
	v_mul_f32_e32 v107, v107, v100
	v_add_f32_e32 v106, 1.0, v112
	v_cndmask_b32_e64 v112, v107, v113, s[6:7]
	v_mul_f32_e32 v113, 0xbfb8aa3b, v37
	v_rcp_f32_e32 v106, v106
	v_exp_f32_e32 v113, v113
	v_mul_f32_e32 v114, 0xbfb8aa3b, v29
	v_exp_f32_e32 v114, v114
	v_mul_f32_e32 v107, v28, v106
	v_add_f32_e32 v113, 1.0, v113
	v_mul_f32_e32 v107, v107, v104
	v_rcp_f32_e32 v115, v113
	v_cndmask_b32_e64 v113, v107, v106, s[6:7]
	v_add_f32_e32 v106, 1.0, v114
	v_rcp_f32_e32 v106, v106
	v_mul_f32_e32 v107, v37, v115
	v_mul_f32_e32 v107, v107, v101
	v_cndmask_b32_e64 v114, v107, v115, s[6:7]
	v_mul_f32_e32 v107, v29, v106
	v_mul_f32_e32 v107, v107, v105
	v_cndmask_b32_e64 v115, v107, v106, s[6:7]
.LBB0_736:
	v_add_u32_e32 v116, 0x80, v156
	v_mov_b64_e32 v[106:107], s[64:65]
	v_mad_i64_i32 v[106:107], s[26:27], v116, s49, v[106:107]
	v_lshl_add_u64 v[106:107], v[158:159], 1, v[106:107]
	s_and_b64 vcc, exec, s[4:5]
	v_cvt_pk_bf16_f32 v116, v108, v110
	v_cvt_pk_bf16_f32 v117, v112, v114
	v_cvt_pk_bf16_f32 v118, v109, v111
	v_cvt_pk_bf16_f32 v119, v113, v115
	global_store_dwordx4 v[106:107], v[116:119], off nt
	s_cbranch_vccnz .LBB0_738
	v_mul_f32_e32 v108, 0xbfb8aa3b, v94
	v_exp_f32_e32 v108, v108
	v_mul_f32_e32 v110, 0xbfb8aa3b, v95
	v_mul_f32_e32 v109, 0xbfb8aa3b, v90
	v_exp_f32_e32 v109, v109
	v_add_f32_e32 v108, 1.0, v108
	v_rcp_f32_e32 v108, v108
	v_add_f32_e32 v109, 1.0, v109
	v_rcp_f32_e32 v109, v109
	v_mul_f32_e32 v94, v94, v108
	v_mul_f32_e32 v94, v94, v98
	v_cndmask_b32_e64 v94, v94, v108, s[6:7]
	v_exp_f32_e32 v108, v110
	v_mul_f32_e32 v110, 0xbfb8aa3b, v91
	v_exp_f32_e32 v110, v110
	v_mul_f32_e32 v90, v90, v109
	v_add_f32_e32 v108, 1.0, v108
	v_rcp_f32_e32 v108, v108
	v_mul_f32_e32 v90, v90, v102
	v_cndmask_b32_e64 v90, v90, v109, s[6:7]
	v_add_f32_e32 v109, 1.0, v110
	v_mul_f32_e32 v95, v95, v108
	v_mul_f32_e32 v95, v95, v99
	v_cndmask_b32_e64 v95, v95, v108, s[6:7]
	v_mul_f32_e32 v108, 0xbfb8aa3b, v96
	v_exp_f32_e32 v108, v108
	v_rcp_f32_e32 v109, v109
	v_mul_f32_e32 v110, 0xbfb8aa3b, v92
	v_exp_f32_e32 v110, v110
	v_add_f32_e32 v108, 1.0, v108
	v_rcp_f32_e32 v108, v108
	v_mul_f32_e32 v91, v91, v109
	v_mul_f32_e32 v91, v91, v103
	v_cndmask_b32_e64 v91, v91, v109, s[6:7]
	v_add_f32_e32 v109, 1.0, v110
	v_mul_f32_e32 v96, v96, v108
	v_rcp_f32_e32 v109, v109
	v_mul_f32_e32 v96, v96, v100
	v_cndmask_b32_e64 v96, v96, v108, s[6:7]
	v_mul_f32_e32 v108, 0xbfb8aa3b, v97
	v_mul_f32_e32 v110, 0xbfb8aa3b, v93
	v_exp_f32_e32 v108, v108
	v_exp_f32_e32 v110, v110
	v_mul_f32_e32 v92, v92, v109
	v_mul_f32_e32 v92, v92, v104
	v_add_f32_e32 v108, 1.0, v108
	v_cndmask_b32_e64 v92, v92, v109, s[6:7]
	v_add_f32_e32 v109, 1.0, v110
	v_rcp_f32_e32 v108, v108
	v_rcp_f32_e32 v109, v109
	v_mul_f32_e32 v97, v97, v108
	v_mul_f32_e32 v93, v93, v109
	v_mul_f32_e32 v97, v97, v101
	v_mul_f32_e32 v93, v93, v105
	v_cndmask_b32_e64 v97, v97, v108, s[6:7]
	v_cndmask_b32_e64 v93, v93, v109, s[6:7]
.LBB0_738:
	v_cvt_pk_bf16_f32 v94, v94, v95
	v_cvt_pk_bf16_f32 v95, v96, v97
	v_cvt_pk_bf16_f32 v96, v90, v91
	v_cvt_pk_bf16_f32 v97, v92, v93
	global_store_dwordx4 v[106:107], v[94:97], off offset:256 nt
	s_and_b64 vcc, exec, s[4:5]
	v_mov_b32_e32 v92, v22
	v_mov_b32_e32 v94, v23
	v_mov_b32_e32 v96, v24
	v_mov_b32_e32 v106, v25
	v_mov_b32_e32 v93, v18
	v_mov_b32_e32 v95, v19
	v_mov_b32_e32 v97, v20
	v_mov_b32_e32 v107, v21
	s_cbranch_vccnz .LBB0_740
	v_mul_f32_e32 v90, 0xbfb8aa3b, v22
	v_exp_f32_e32 v90, v90
	v_mul_f32_e32 v91, 0xbfb8aa3b, v18
	v_exp_f32_e32 v91, v91
	v_mul_f32_e32 v93, 0xbfb8aa3b, v23
	v_add_f32_e32 v90, 1.0, v90
	v_rcp_f32_e32 v90, v90
	v_add_f32_e32 v91, 1.0, v91
	v_rcp_f32_e32 v91, v91
	v_mul_f32_e32 v95, 0xbfb8aa3b, v24
	v_mul_f32_e32 v92, v22, v90
	v_mul_f32_e32 v92, v92, v98
	v_mul_f32_e32 v94, v18, v91
	v_cndmask_b32_e64 v92, v92, v90, s[6:7]
	v_exp_f32_e32 v90, v93
	v_mul_f32_e32 v93, v94, v102
	v_mul_f32_e32 v94, 0xbfb8aa3b, v19
	v_exp_f32_e32 v94, v94
	v_add_f32_e32 v90, 1.0, v90
	v_exp_f32_e32 v95, v95
	v_rcp_f32_e32 v90, v90
	v_cndmask_b32_e64 v93, v93, v91, s[6:7]
	v_add_f32_e32 v91, 1.0, v94
	v_rcp_f32_e32 v91, v91
	v_add_f32_e32 v95, 1.0, v95
	v_mul_f32_e32 v94, v23, v90
	v_rcp_f32_e32 v97, v95
	v_mul_f32_e32 v94, v94, v99
	v_mul_f32_e32 v96, 0xbfb8aa3b, v20
	v_cndmask_b32_e64 v94, v94, v90, s[6:7]
	v_mul_f32_e32 v90, v19, v91
	v_exp_f32_e32 v96, v96
	v_mul_f32_e32 v90, v90, v103
	v_cndmask_b32_e64 v95, v90, v91, s[6:7]
	v_mul_f32_e32 v91, v24, v97
	v_mul_f32_e32 v91, v91, v100
	v_add_f32_e32 v90, 1.0, v96
	v_cndmask_b32_e64 v96, v91, v97, s[6:7]
	v_mul_f32_e32 v97, 0xbfb8aa3b, v25
	v_rcp_f32_e32 v90, v90
	v_exp_f32_e32 v97, v97
	v_mul_f32_e32 v106, 0xbfb8aa3b, v21
	v_exp_f32_e32 v106, v106
	v_mul_f32_e32 v91, v20, v90
	v_add_f32_e32 v97, 1.0, v97
	v_mul_f32_e32 v91, v91, v104
	v_rcp_f32_e32 v107, v97
	v_cndmask_b32_e64 v97, v91, v90, s[6:7]
	v_add_f32_e32 v90, 1.0, v106
	v_rcp_f32_e32 v90, v90
	v_mul_f32_e32 v91, v25, v107
	v_mul_f32_e32 v91, v91, v101
	v_cndmask_b32_e64 v106, v91, v107, s[6:7]
	v_mul_f32_e32 v91, v21, v90
	v_mul_f32_e32 v91, v91, v105
	v_cndmask_b32_e64 v107, v91, v90, s[6:7]
.LBB0_740:
	v_add_u32_e32 v108, 0x90, v156
	v_mov_b64_e32 v[90:91], s[64:65]
	v_mad_i64_i32 v[90:91], s[26:27], v108, s49, v[90:91]
	v_lshl_add_u64 v[90:91], v[158:159], 1, v[90:91]
	s_and_b64 vcc, exec, s[4:5]
	v_cvt_pk_bf16_f32 v108, v92, v94
	v_cvt_pk_bf16_f32 v109, v96, v106
	v_cvt_pk_bf16_f32 v110, v93, v95
	v_cvt_pk_bf16_f32 v111, v97, v107
	global_store_dwordx4 v[90:91], v[108:111], off nt
	s_cbranch_vccnz .LBB0_742
	v_mul_f32_e32 v92, 0xbfb8aa3b, v86
	v_exp_f32_e32 v92, v92
	v_mul_f32_e32 v94, 0xbfb8aa3b, v87
	v_mul_f32_e32 v93, 0xbfb8aa3b, v82
	v_exp_f32_e32 v93, v93
	v_add_f32_e32 v92, 1.0, v92
	v_rcp_f32_e32 v92, v92
	v_add_f32_e32 v93, 1.0, v93
	v_rcp_f32_e32 v93, v93
	v_mul_f32_e32 v86, v86, v92
	v_mul_f32_e32 v86, v86, v98
	v_cndmask_b32_e64 v86, v86, v92, s[6:7]
	v_exp_f32_e32 v92, v94
	v_mul_f32_e32 v94, 0xbfb8aa3b, v83
	v_exp_f32_e32 v94, v94
	v_mul_f32_e32 v82, v82, v93
	v_add_f32_e32 v92, 1.0, v92
	v_rcp_f32_e32 v92, v92
	v_mul_f32_e32 v82, v82, v102
	v_cndmask_b32_e64 v82, v82, v93, s[6:7]
	v_add_f32_e32 v93, 1.0, v94
	v_mul_f32_e32 v87, v87, v92
	v_mul_f32_e32 v87, v87, v99
	v_cndmask_b32_e64 v87, v87, v92, s[6:7]
	v_mul_f32_e32 v92, 0xbfb8aa3b, v88
	v_exp_f32_e32 v92, v92
	v_rcp_f32_e32 v93, v93
	v_mul_f32_e32 v94, 0xbfb8aa3b, v84
	v_exp_f32_e32 v94, v94
	v_add_f32_e32 v92, 1.0, v92
	v_rcp_f32_e32 v92, v92
	v_mul_f32_e32 v83, v83, v93
	v_mul_f32_e32 v83, v83, v103
	v_cndmask_b32_e64 v83, v83, v93, s[6:7]
	v_add_f32_e32 v93, 1.0, v94
	v_mul_f32_e32 v88, v88, v92
	v_rcp_f32_e32 v93, v93
	v_mul_f32_e32 v88, v88, v100
	v_cndmask_b32_e64 v88, v88, v92, s[6:7]
	v_mul_f32_e32 v92, 0xbfb8aa3b, v89
	v_mul_f32_e32 v94, 0xbfb8aa3b, v85
	v_exp_f32_e32 v92, v92
	v_exp_f32_e32 v94, v94
	v_mul_f32_e32 v84, v84, v93
	v_mul_f32_e32 v84, v84, v104
	v_add_f32_e32 v92, 1.0, v92
	v_cndmask_b32_e64 v84, v84, v93, s[6:7]
	v_add_f32_e32 v93, 1.0, v94
	v_rcp_f32_e32 v92, v92
	v_rcp_f32_e32 v93, v93
	v_mul_f32_e32 v89, v89, v92
	v_mul_f32_e32 v85, v85, v93
	v_mul_f32_e32 v89, v89, v101
	v_mul_f32_e32 v85, v85, v105
	v_cndmask_b32_e64 v89, v89, v92, s[6:7]
	v_cndmask_b32_e64 v85, v85, v93, s[6:7]
.LBB0_742:
	v_cvt_pk_bf16_f32 v86, v86, v87
	v_cvt_pk_bf16_f32 v87, v88, v89
	v_cvt_pk_bf16_f32 v88, v82, v83
	v_cvt_pk_bf16_f32 v89, v84, v85
	global_store_dwordx4 v[90:91], v[86:89], off offset:256 nt
	s_and_b64 vcc, exec, s[4:5]
	v_mov_b32_e32 v84, v14
	v_mov_b32_e32 v86, v15
	v_mov_b32_e32 v88, v16
	v_mov_b32_e32 v90, v17
	v_mov_b32_e32 v85, v10
	v_mov_b32_e32 v87, v11
	v_mov_b32_e32 v89, v12
	v_mov_b32_e32 v91, v13
	s_cbranch_vccnz .LBB0_744
	v_mul_f32_e32 v82, 0xbfb8aa3b, v14
	v_exp_f32_e32 v82, v82
	v_mul_f32_e32 v83, 0xbfb8aa3b, v10
	v_exp_f32_e32 v83, v83
	v_mul_f32_e32 v85, 0xbfb8aa3b, v15
	v_add_f32_e32 v82, 1.0, v82
	v_rcp_f32_e32 v82, v82
	v_add_f32_e32 v83, 1.0, v83
	v_rcp_f32_e32 v83, v83
	v_mul_f32_e32 v87, 0xbfb8aa3b, v16
	v_mul_f32_e32 v84, v14, v82
	v_mul_f32_e32 v84, v84, v98
	v_mul_f32_e32 v86, v10, v83
	v_cndmask_b32_e64 v84, v84, v82, s[6:7]
	v_exp_f32_e32 v82, v85
	v_mul_f32_e32 v85, v86, v102
	v_mul_f32_e32 v86, 0xbfb8aa3b, v11
	v_exp_f32_e32 v86, v86
	v_add_f32_e32 v82, 1.0, v82
	v_exp_f32_e32 v87, v87
	v_rcp_f32_e32 v82, v82
	v_cndmask_b32_e64 v85, v85, v83, s[6:7]
	v_add_f32_e32 v83, 1.0, v86
	v_rcp_f32_e32 v83, v83
	v_add_f32_e32 v87, 1.0, v87
	v_mul_f32_e32 v86, v15, v82
	v_rcp_f32_e32 v89, v87
	v_mul_f32_e32 v86, v86, v99
	v_mul_f32_e32 v88, 0xbfb8aa3b, v12
	v_cndmask_b32_e64 v86, v86, v82, s[6:7]
	v_mul_f32_e32 v82, v11, v83
	v_exp_f32_e32 v88, v88
	v_mul_f32_e32 v82, v82, v103
	v_cndmask_b32_e64 v87, v82, v83, s[6:7]
	v_mul_f32_e32 v83, v16, v89
	v_mul_f32_e32 v83, v83, v100
	v_add_f32_e32 v82, 1.0, v88
	v_cndmask_b32_e64 v88, v83, v89, s[6:7]
	v_mul_f32_e32 v89, 0xbfb8aa3b, v17
	v_rcp_f32_e32 v82, v82
	v_exp_f32_e32 v89, v89
	v_mul_f32_e32 v90, 0xbfb8aa3b, v13
	v_exp_f32_e32 v90, v90
	v_mul_f32_e32 v83, v12, v82
	v_add_f32_e32 v89, 1.0, v89
	v_mul_f32_e32 v83, v83, v104
	v_rcp_f32_e32 v91, v89
	v_cndmask_b32_e64 v89, v83, v82, s[6:7]
	v_add_f32_e32 v82, 1.0, v90
	v_rcp_f32_e32 v82, v82
	v_mul_f32_e32 v83, v17, v91
	v_mul_f32_e32 v83, v83, v101
	v_cndmask_b32_e64 v90, v83, v91, s[6:7]
	v_mul_f32_e32 v83, v13, v82
	v_mul_f32_e32 v83, v83, v105
	v_cndmask_b32_e64 v91, v83, v82, s[6:7]
.LBB0_744:
	v_add_u32_e32 v92, 0xa0, v156
	v_mov_b64_e32 v[82:83], s[64:65]
	v_mad_i64_i32 v[82:83], s[26:27], v92, s49, v[82:83]
	v_lshl_add_u64 v[82:83], v[158:159], 1, v[82:83]
	s_and_b64 vcc, exec, s[4:5]
	v_cvt_pk_bf16_f32 v92, v84, v86
	v_cvt_pk_bf16_f32 v93, v88, v90
	v_cvt_pk_bf16_f32 v94, v85, v87
	v_cvt_pk_bf16_f32 v95, v89, v91
	global_store_dwordx4 v[82:83], v[92:95], off nt
	s_cbranch_vccnz .LBB0_746
	v_mul_f32_e32 v84, 0xbfb8aa3b, v78
	v_exp_f32_e32 v84, v84
	v_mul_f32_e32 v86, 0xbfb8aa3b, v79
	v_mul_f32_e32 v85, 0xbfb8aa3b, v74
	v_exp_f32_e32 v85, v85
	v_add_f32_e32 v84, 1.0, v84
	v_rcp_f32_e32 v84, v84
	v_add_f32_e32 v85, 1.0, v85
	v_rcp_f32_e32 v85, v85
	v_mul_f32_e32 v78, v78, v84
	v_mul_f32_e32 v78, v78, v98
	v_cndmask_b32_e64 v78, v78, v84, s[6:7]
	v_exp_f32_e32 v84, v86
	v_mul_f32_e32 v86, 0xbfb8aa3b, v75
	v_exp_f32_e32 v86, v86
	v_mul_f32_e32 v74, v74, v85
	v_add_f32_e32 v84, 1.0, v84
	v_rcp_f32_e32 v84, v84
	v_mul_f32_e32 v74, v74, v102
	v_cndmask_b32_e64 v74, v74, v85, s[6:7]
	v_add_f32_e32 v85, 1.0, v86
	v_mul_f32_e32 v79, v79, v84
	v_mul_f32_e32 v79, v79, v99
	v_cndmask_b32_e64 v79, v79, v84, s[6:7]
	v_mul_f32_e32 v84, 0xbfb8aa3b, v80
	v_exp_f32_e32 v84, v84
	v_rcp_f32_e32 v85, v85
	v_mul_f32_e32 v86, 0xbfb8aa3b, v76
	v_exp_f32_e32 v86, v86
	v_add_f32_e32 v84, 1.0, v84
	v_rcp_f32_e32 v84, v84
	v_mul_f32_e32 v75, v75, v85
	v_mul_f32_e32 v75, v75, v103
	v_cndmask_b32_e64 v75, v75, v85, s[6:7]
	v_add_f32_e32 v85, 1.0, v86
	v_mul_f32_e32 v80, v80, v84
	v_rcp_f32_e32 v85, v85
	v_mul_f32_e32 v80, v80, v100
	v_cndmask_b32_e64 v80, v80, v84, s[6:7]
	v_mul_f32_e32 v84, 0xbfb8aa3b, v81
	v_mul_f32_e32 v86, 0xbfb8aa3b, v77
	v_exp_f32_e32 v84, v84
	v_exp_f32_e32 v86, v86
	v_mul_f32_e32 v76, v76, v85
	v_mul_f32_e32 v76, v76, v104
	v_add_f32_e32 v84, 1.0, v84
	v_cndmask_b32_e64 v76, v76, v85, s[6:7]
	v_add_f32_e32 v85, 1.0, v86
	v_rcp_f32_e32 v84, v84
	v_rcp_f32_e32 v85, v85
	v_mul_f32_e32 v81, v81, v84
	v_mul_f32_e32 v77, v77, v85
	v_mul_f32_e32 v81, v81, v101
	v_mul_f32_e32 v77, v77, v105
	v_cndmask_b32_e64 v81, v81, v84, s[6:7]
	v_cndmask_b32_e64 v77, v77, v85, s[6:7]
.LBB0_746:
	v_cvt_pk_bf16_f32 v78, v78, v79
	v_cvt_pk_bf16_f32 v79, v80, v81
	v_cvt_pk_bf16_f32 v80, v74, v75
	v_cvt_pk_bf16_f32 v81, v76, v77
	global_store_dwordx4 v[82:83], v[78:81], off offset:256 nt
	s_and_b64 vcc, exec, s[4:5]
	v_mov_b32_e32 v76, v6
	v_mov_b32_e32 v78, v7
	v_mov_b32_e32 v80, v8
	v_mov_b32_e32 v82, v9
	v_mov_b32_e32 v77, v2
	v_mov_b32_e32 v79, v3
	v_mov_b32_e32 v81, v4
	v_mov_b32_e32 v83, v5
	s_cbranch_vccnz .LBB0_748
	v_mul_f32_e32 v74, 0xbfb8aa3b, v6
	v_exp_f32_e32 v74, v74
	v_mul_f32_e32 v75, 0xbfb8aa3b, v2
	v_exp_f32_e32 v75, v75
	v_mul_f32_e32 v77, 0xbfb8aa3b, v7
	v_add_f32_e32 v74, 1.0, v74
	v_rcp_f32_e32 v74, v74
	v_add_f32_e32 v75, 1.0, v75
	v_rcp_f32_e32 v75, v75
	v_mul_f32_e32 v79, 0xbfb8aa3b, v8
	v_mul_f32_e32 v76, v6, v74
	v_mul_f32_e32 v76, v76, v98
	v_mul_f32_e32 v78, v2, v75
	v_cndmask_b32_e64 v76, v76, v74, s[6:7]
	v_exp_f32_e32 v74, v77
	v_mul_f32_e32 v77, v78, v102
	v_mul_f32_e32 v78, 0xbfb8aa3b, v3
	v_exp_f32_e32 v78, v78
	v_add_f32_e32 v74, 1.0, v74
	v_exp_f32_e32 v79, v79
	v_rcp_f32_e32 v74, v74
	v_cndmask_b32_e64 v77, v77, v75, s[6:7]
	v_add_f32_e32 v75, 1.0, v78
	v_rcp_f32_e32 v75, v75
	v_add_f32_e32 v79, 1.0, v79
	v_mul_f32_e32 v78, v7, v74
	v_rcp_f32_e32 v81, v79
	v_mul_f32_e32 v78, v78, v99
	v_mul_f32_e32 v80, 0xbfb8aa3b, v4
	v_cndmask_b32_e64 v78, v78, v74, s[6:7]
	v_mul_f32_e32 v74, v3, v75
	v_exp_f32_e32 v80, v80
	v_mul_f32_e32 v74, v74, v103
	v_cndmask_b32_e64 v79, v74, v75, s[6:7]
	v_mul_f32_e32 v75, v8, v81
	v_mul_f32_e32 v75, v75, v100
	v_add_f32_e32 v74, 1.0, v80
	v_cndmask_b32_e64 v80, v75, v81, s[6:7]
	v_mul_f32_e32 v81, 0xbfb8aa3b, v9
	v_rcp_f32_e32 v74, v74
	v_exp_f32_e32 v81, v81
	v_mul_f32_e32 v82, 0xbfb8aa3b, v5
	v_exp_f32_e32 v82, v82
	v_mul_f32_e32 v75, v4, v74
	v_add_f32_e32 v81, 1.0, v81
	v_mul_f32_e32 v75, v75, v104
	v_rcp_f32_e32 v83, v81
	v_cndmask_b32_e64 v81, v75, v74, s[6:7]
	v_add_f32_e32 v74, 1.0, v82
	v_rcp_f32_e32 v74, v74
	v_mul_f32_e32 v75, v9, v83
	v_mul_f32_e32 v75, v75, v101
	v_cndmask_b32_e64 v82, v75, v83, s[6:7]
	v_mul_f32_e32 v75, v5, v74
	v_mul_f32_e32 v75, v75, v105
	v_cndmask_b32_e64 v83, v75, v74, s[6:7]
.LBB0_748:
	v_add_u32_e32 v84, 0xb0, v156
	v_mov_b64_e32 v[74:75], s[64:65]
	v_mad_i64_i32 v[74:75], s[26:27], v84, s49, v[74:75]
	v_lshl_add_u64 v[74:75], v[158:159], 1, v[74:75]
	s_and_b64 vcc, exec, s[4:5]
	v_cvt_pk_bf16_f32 v84, v76, v78
	v_cvt_pk_bf16_f32 v85, v80, v82
	v_cvt_pk_bf16_f32 v86, v77, v79
	v_cvt_pk_bf16_f32 v87, v81, v83
	global_store_dwordx4 v[74:75], v[84:87], off nt
	s_cbranch_vccnz .LBB0_750
	v_mul_f32_e32 v76, 0xbfb8aa3b, v38
	v_exp_f32_e32 v76, v76
	v_mul_f32_e32 v78, 0xbfb8aa3b, v39
	v_mul_f32_e32 v77, 0xbfb8aa3b, v30
	v_exp_f32_e32 v77, v77
	v_add_f32_e32 v76, 1.0, v76
	v_rcp_f32_e32 v76, v76
	v_add_f32_e32 v77, 1.0, v77
	v_rcp_f32_e32 v77, v77
	v_mul_f32_e32 v38, v38, v76
	v_mul_f32_e32 v38, v38, v98
	v_cndmask_b32_e64 v38, v38, v76, s[6:7]
	v_exp_f32_e32 v76, v78
	v_mul_f32_e32 v78, 0xbfb8aa3b, v31
	v_exp_f32_e32 v78, v78
	v_mul_f32_e32 v30, v30, v77
	v_add_f32_e32 v76, 1.0, v76
	v_rcp_f32_e32 v76, v76
	v_mul_f32_e32 v30, v30, v102
	v_cndmask_b32_e64 v30, v30, v77, s[6:7]
	v_add_f32_e32 v77, 1.0, v78
	v_mul_f32_e32 v39, v39, v76
	v_mul_f32_e32 v39, v39, v99
	v_cndmask_b32_e64 v39, v39, v76, s[6:7]
	v_mul_f32_e32 v76, 0xbfb8aa3b, v40
	v_exp_f32_e32 v76, v76
	v_rcp_f32_e32 v77, v77
	v_mul_f32_e32 v78, 0xbfb8aa3b, v32
	v_exp_f32_e32 v78, v78
	v_add_f32_e32 v76, 1.0, v76
	v_rcp_f32_e32 v76, v76
	v_mul_f32_e32 v31, v31, v77
	v_mul_f32_e32 v31, v31, v103
	v_cndmask_b32_e64 v31, v31, v77, s[6:7]
	v_add_f32_e32 v77, 1.0, v78
	v_mul_f32_e32 v40, v40, v76
	v_rcp_f32_e32 v77, v77
	v_mul_f32_e32 v40, v40, v100
	v_cndmask_b32_e64 v40, v40, v76, s[6:7]
	v_mul_f32_e32 v76, 0xbfb8aa3b, v41
	v_mul_f32_e32 v78, 0xbfb8aa3b, v33
	v_exp_f32_e32 v76, v76
	v_exp_f32_e32 v78, v78
	v_mul_f32_e32 v32, v32, v77
	v_mul_f32_e32 v32, v32, v104
	v_add_f32_e32 v76, 1.0, v76
	v_cndmask_b32_e64 v32, v32, v77, s[6:7]
	v_add_f32_e32 v77, 1.0, v78
	v_rcp_f32_e32 v76, v76
	v_rcp_f32_e32 v77, v77
	v_mul_f32_e32 v41, v41, v76
	v_mul_f32_e32 v33, v33, v77
	v_mul_f32_e32 v41, v41, v101
	v_mul_f32_e32 v33, v33, v105
	v_cndmask_b32_e64 v41, v41, v76, s[6:7]
	v_cndmask_b32_e64 v33, v33, v77, s[6:7]
